# hazard-slot fill: s_mov m0 moved ahead of the address add in 38 LDS-DMA groups, s_nop dropped (on v25)
# baseline (speedup 1.0000x reference)
; #define PG8_STAGE(bufoff, gbase, voff) do { _Pragma("unroll") for (int _i = 0; _i < 2; ++_i) \
;         __builtin_amdgcn_global_load_lds((const unsigned*)((const char*)(gbase) + (voff)[_i]), (PG8_LAS unsigned*)(lds + (bufoff) + ldsw + _i * 8192), 16, 0, 0); } while (0)
; #define PG8_LDA(dst, b, h) do { _Pragma("unroll") for (int m = 0; m < 4; ++m) _Pragma("unroll") for (int k = 0; k < 2; ++k) dst[m][k] = *(const PG8_LAS bf16x8*)(lds + PG8_SA(b, h) + aoff + m * 2048 + k * 1024); } while (0)
; #define PG8_MMA(ai, bj, At, Bt) do { __builtin_amdgcn_s_setprio(1); _Pragma("unroll") for (int m = 0; m < 4; ++m) _Pragma("unroll") for (int n = 0; n < 2; ++n) _Pragma("unroll") for (int k = 0; k < 2; ++k) \
;         acc[ai][bj][m][n] = __builtin_amdgcn_mfma_f32_16x16x32_bf16(Bt[n][k], At[m][k], acc[ai][bj][m][n], 0, 0, 0); __builtin_amdgcn_s_setprio(0); } while (0)
; #define PG8_WAIT_V(n) asm volatile("s_waitcnt vmcnt(" #n ")" ::: "memory")
; #define PG8_WAIT_L(n) asm volatile("s_waitcnt lgkmcnt(" #n ")" ::: "memory")
; #define PG8_BAR __builtin_amdgcn_s_barrier()
; #define PG8_SCHED __builtin_amdgcn_sched_barrier(0)
; template <class Epi, class Sched, bool ALIGN_EPI = false, bool SP2 = false>
; __device__ __forceinline__ void gemm_phase(PG8_LAS unsigned char* lds, const Gemm g, const Sched& S, const Epi& E, const int tid_) {
;     ...
;             PG8_WAIT_V(8); PG8_WAIT_L(0); PG8_BAR; PG8_MMA(0, 0, At, B0); PG8_MMA(0, 1, At, B1); PG8_BAR; PG8_SCHED;
;             PG8_LDA(At, 0, 1); PG8_STAGE(PG8_SB(0, 0), b2, voffB); PG8_STAGE(PG8_SB(0, 1), b2 + hstepB, voffB); PG8_STAGE(PG8_SA(0, 0), a2, voffA);
;             PG8_WAIT_V(8); PG8_WAIT_L(0); PG8_BAR; PG8_MMA(1, 0, At, B0); PG8_MMA(1, 1, At, B1); PG8_BAR; PG8_SCHED;
.Lpeel1_w1:
	s_waitcnt lgkmcnt(0)
	s_barrier
	s_waitcnt lgkmcnt(0)
	v_mfma_f32_16x16x32_bf16 v[128:131], v[132:135], v[188:191], 0
	v_mfma_f32_16x16x32_bf16 v[120:123], v[150:153], v[188:191], 0
	v_mfma_f32_16x16x32_bf16 v[112:115], v[132:135], v[196:199], 0
	v_mfma_f32_16x16x32_bf16 v[104:107], v[150:153], v[196:199], 0
	v_mfma_f32_16x16x32_bf16 v[96:99], v[132:135], v[204:207], 0
	v_mfma_f32_16x16x32_bf16 v[88:91], v[150:153], v[204:207], 0
	v_mfma_f32_16x16x32_bf16 v[80:83], v[132:135], v[212:215], 0
	v_mfma_f32_16x16x32_bf16 v[72:75], v[150:153], v[212:215], 0
	v_mfma_f32_16x16x32_bf16 v[128:131], v[146:149], v[192:195], v[128:131]
	v_mfma_f32_16x16x32_bf16 v[120:123], v[154:157], v[192:195], v[120:123]
	v_mfma_f32_16x16x32_bf16 v[112:115], v[146:149], v[200:203], v[112:115]
	v_mfma_f32_16x16x32_bf16 v[104:107], v[154:157], v[200:203], v[104:107]
	v_mfma_f32_16x16x32_bf16 v[96:99], v[146:149], v[208:211], v[96:99]
	v_mfma_f32_16x16x32_bf16 v[88:91], v[154:157], v[208:211], v[88:91]
	v_mfma_f32_16x16x32_bf16 v[80:83], v[146:149], v[216:219], v[80:83]
	v_mfma_f32_16x16x32_bf16 v[72:75], v[154:157], v[216:219], v[72:75]
	v_mfma_f32_16x16x32_bf16 v[124:127], v[158:161], v[188:191], 0
	v_mfma_f32_16x16x32_bf16 v[116:119], v[170:173], v[188:191], 0
	v_mfma_f32_16x16x32_bf16 v[108:111], v[158:161], v[196:199], 0
	v_mfma_f32_16x16x32_bf16 v[100:103], v[170:173], v[196:199], 0
	v_mfma_f32_16x16x32_bf16 v[92:95], v[158:161], v[204:207], 0
	v_mfma_f32_16x16x32_bf16 v[84:87], v[170:173], v[204:207], 0
	v_mfma_f32_16x16x32_bf16 v[76:79], v[158:161], v[212:215], 0
	v_mfma_f32_16x16x32_bf16 v[68:71], v[170:173], v[212:215], 0
	v_mfma_f32_16x16x32_bf16 v[124:127], v[166:169], v[192:195], v[124:127]
	v_mfma_f32_16x16x32_bf16 v[116:119], v[174:177], v[192:195], v[116:119]
	v_mfma_f32_16x16x32_bf16 v[108:111], v[166:169], v[200:203], v[108:111]
	v_mfma_f32_16x16x32_bf16 v[100:103], v[174:177], v[200:203], v[100:103]
	v_mfma_f32_16x16x32_bf16 v[92:95], v[166:169], v[208:211], v[92:95]
	v_mfma_f32_16x16x32_bf16 v[84:87], v[174:177], v[208:211], v[84:87]
	v_mfma_f32_16x16x32_bf16 v[76:79], v[166:169], v[216:219], v[76:79]
	v_mfma_f32_16x16x32_bf16 v[68:71], v[174:177], v[216:219], v[68:71]
	s_barrier
	s_mov_b32 m0, s35
	v_lshl_add_u64 v[178:179], s[26:27], 0, v[2:3]
	s_add_u32 s58, s26, 0x40000
	ds_read_b128 v[188:191], v165 offset:16384
	ds_read_b128 v[192:195], v165 offset:17408
	ds_read_b128 v[196:199], v165 offset:18432
	ds_read_b128 v[200:203], v165 offset:19456
	ds_read_b128 v[204:207], v165 offset:20480
	ds_read_b128 v[208:211], v165 offset:21504
	ds_read_b128 v[212:215], v165 offset:22528
	ds_read_b128 v[216:219], v165 offset:23552
	global_load_lds_dwordx4 v[178:179], off
	v_lshl_add_u64 v[220:221], s[26:27], 0, v[0:1]
	s_mov_b32 m0, s36
	s_addc_u32 s59, s27, 0
	global_load_lds_dwordx4 v[220:221], off
	v_lshl_add_u64 v[222:223], s[58:59], 0, v[2:3]
	s_mov_b32 m0, s38
	v_lshl_add_u64 v[224:225], s[28:29], 0, v[136:137]
	global_load_lds_dwordx4 v[222:223], off
	s_mov_b32 m0, s39
	v_lshl_add_u64 v[222:223], s[58:59], 0, v[0:1]
	global_load_lds_dwordx4 v[222:223], off
	s_mov_b32 m0, s40
	v_lshl_add_u64 v[222:223], s[28:29], 0, v[138:139]
	global_load_lds_dwordx4 v[222:223], off
	s_mov_b32 m0, s41
	s_nop 0
	global_load_lds_dwordx4 v[224:225], off
	s_cmp_lg_u32 s53, 1
	s_cbranch_scc1 .Lpeel1_w2
	s_waitcnt vmcnt(8)
.Lpeel1_w2:
	s_waitcnt lgkmcnt(0)
	s_barrier
	s_waitcnt lgkmcnt(0)
	v_mfma_f32_16x16x32_bf16 v[64:67], v[132:135], v[188:191], 0
	v_mfma_f32_16x16x32_bf16 v[56:59], v[150:153], v[188:191], 0
	v_mfma_f32_16x16x32_bf16 v[48:51], v[132:135], v[196:199], 0
	v_mfma_f32_16x16x32_bf16 v[40:43], v[150:153], v[196:199], 0
	v_mfma_f32_16x16x32_bf16 v[32:35], v[132:135], v[204:207], 0
	v_mfma_f32_16x16x32_bf16 v[24:27], v[150:153], v[204:207], 0
	v_mfma_f32_16x16x32_bf16 v[16:19], v[132:135], v[212:215], 0
	v_mfma_f32_16x16x32_bf16 v[8:11], v[150:153], v[212:215], 0
	v_mfma_f32_16x16x32_bf16 v[64:67], v[146:149], v[192:195], v[64:67]
	v_mfma_f32_16x16x32_bf16 v[56:59], v[154:157], v[192:195], v[56:59]
	v_mfma_f32_16x16x32_bf16 v[48:51], v[146:149], v[200:203], v[48:51]
	v_mfma_f32_16x16x32_bf16 v[40:43], v[154:157], v[200:203], v[40:43]
	v_mfma_f32_16x16x32_bf16 v[32:35], v[146:149], v[208:211], v[32:35]
	v_mfma_f32_16x16x32_bf16 v[24:27], v[154:157], v[208:211], v[24:27]
	v_mfma_f32_16x16x32_bf16 v[16:19], v[146:149], v[216:219], v[16:19]
	v_mfma_f32_16x16x32_bf16 v[8:11], v[154:157], v[216:219], v[8:11]
	v_mfma_f32_16x16x32_bf16 v[60:63], v[158:161], v[188:191], 0
	v_mfma_f32_16x16x32_bf16 v[52:55], v[170:173], v[188:191], 0
	v_mfma_f32_16x16x32_bf16 v[44:47], v[158:161], v[196:199], 0
	v_mfma_f32_16x16x32_bf16 v[36:39], v[170:173], v[196:199], 0
	v_mfma_f32_16x16x32_bf16 v[28:31], v[158:161], v[204:207], 0
	v_mfma_f32_16x16x32_bf16 v[20:23], v[170:173], v[204:207], 0
	v_mfma_f32_16x16x32_bf16 v[12:15], v[158:161], v[212:215], 0
	v_mfma_f32_16x16x32_bf16 v[4:7], v[170:173], v[212:215], 0
	v_mfma_f32_16x16x32_bf16 v[60:63], v[166:169], v[192:195], v[60:63]
	v_mfma_f32_16x16x32_bf16 v[52:55], v[174:177], v[192:195], v[52:55]
	v_mfma_f32_16x16x32_bf16 v[44:47], v[166:169], v[200:203], v[44:47]
	v_mfma_f32_16x16x32_bf16 v[36:39], v[174:177], v[200:203], v[36:39]
	v_mfma_f32_16x16x32_bf16 v[28:31], v[166:169], v[208:211], v[28:31]
	v_mfma_f32_16x16x32_bf16 v[20:23], v[174:177], v[208:211], v[20:23]
	v_mfma_f32_16x16x32_bf16 v[12:15], v[166:169], v[216:219], v[12:15]
	v_mfma_f32_16x16x32_bf16 v[4:7], v[174:177], v[216:219], v[4:7]
	s_barrier
; #define PG8_STAGE(bufoff, gbase, voff) do { _Pragma("unroll") for (int _i = 0; _i < 2; ++_i) \
;         __builtin_amdgcn_global_load_lds((const unsigned*)((const char*)(gbase) + (voff)[_i]), (PG8_LAS unsigned*)(lds + (bufoff) + ldsw + _i * 8192), 16, 0, 0); } while (0)
; #define PG8_LDA(dst, b, h) do { _Pragma("unroll") for (int m = 0; m < 4; ++m) _Pragma("unroll") for (int k = 0; k < 2; ++k) dst[m][k] = *(const PG8_LAS bf16x8*)(lds + PG8_SA(b, h) + aoff + m * 2048 + k * 1024); } while (0)
; #define PG8_LDB(dst, b, h) do { _Pragma("unroll") for (int n = 0; n < 2; ++n) _Pragma("unroll") for (int k = 0; k < 2; ++k) dst[n][k] = *(const PG8_LAS bf16x8*)(lds + PG8_SB(b, h) + boff + n * 2048 + k * 1024); } while (0)
; #define PG8_MMA(ai, bj, At, Bt) do { __builtin_amdgcn_s_setprio(1); _Pragma("unroll") for (int m = 0; m < 4; ++m) _Pragma("unroll") for (int n = 0; n < 2; ++n) _Pragma("unroll") for (int k = 0; k < 2; ++k) \
;         acc[ai][bj][m][n] = __builtin_amdgcn_mfma_f32_16x16x32_bf16(Bt[n][k], At[m][k], acc[ai][bj][m][n], 0, 0, 0); __builtin_amdgcn_s_setprio(0); } while (0)
; #define PG8_WAIT_V(n) asm volatile("s_waitcnt vmcnt(" #n ")" ::: "memory")
; #define PG8_WAIT_L(n) asm volatile("s_waitcnt lgkmcnt(" #n ")" ::: "memory")
; #define PG8_BAR __builtin_amdgcn_s_barrier()
; #define PG8_SCHED __builtin_amdgcn_sched_barrier(0)
; template <class Epi, class Sched, bool ALIGN_EPI = false, bool SP2 = false>
; __device__ __forceinline__ void gemm_phase(PG8_LAS unsigned char* lds, const Gemm g, const Sched& S, const Epi& E, const int tid_) {
;     ...
;             PG8_LDB(B0, 1, 0); PG8_LDB(B1, 1, 1); PG8_SCHED; PG8_LDA(At, 1, 0); PG8_STAGE(PG8_SA(0, 1), a2 + hstep, voffA);
;             PG8_WAIT_V(8); PG8_WAIT_L(0); PG8_BAR; PG8_MMA(0, 0, At, B0); PG8_MMA(0, 1, At, B1); PG8_BAR; PG8_SCHED;
;             PG8_LDA(At, 1, 1); PG8_STAGE(PG8_SB(1, 0), b3, voffB); PG8_STAGE(PG8_SB(1, 1), b3 + hstepB, voffB); PG8_STAGE(PG8_SA(1, 0), a3, voffA);
;             PG8_WAIT_V(8); PG8_WAIT_L(0); PG8_BAR; PG8_MMA(1, 0, At, B0); PG8_MMA(1, 1, At, B1); PG8_BAR; PG8_SCHED;
	v_add_u32_e32 v154, s44, v163
	v_add_u32_e32 v174, s49, v163
	ds_read_b128 v[132:135], v154
	ds_read_b128 v[146:149], v154 offset:1024
	ds_read_b128 v[150:153], v154 offset:2048
	ds_read_b128 v[154:157], v154 offset:3072
	ds_read_b128 v[158:161], v174
	ds_read_b128 v[166:169], v174 offset:1024
	ds_read_b128 v[170:173], v174 offset:2048
	ds_read_b128 v[174:177], v174 offset:3072
	s_add_u32 s28, s28, 0x40000
	s_addc_u32 s29, s29, 0
	s_mov_b32 m0, s42
	v_lshl_add_u64 v[226:227], s[28:29], 0, v[138:139]
	ds_read_b128 v[188:191], v165 offset:32768
	ds_read_b128 v[192:195], v165 offset:33792
	ds_read_b128 v[196:199], v165 offset:34816
	ds_read_b128 v[200:203], v165 offset:35840
	ds_read_b128 v[204:207], v165 offset:36864
	ds_read_b128 v[208:211], v165 offset:37888
	ds_read_b128 v[212:215], v165 offset:38912
	ds_read_b128 v[216:219], v165 offset:39936
	global_load_lds_dwordx4 v[226:227], off
	s_mov_b32 m0, s43
	v_lshl_add_u64 v[226:227], s[28:29], 0, v[136:137]
	global_load_lds_dwordx4 v[226:227], off
	s_waitcnt vmcnt(8)
	s_waitcnt lgkmcnt(0)
	s_barrier
	s_waitcnt lgkmcnt(0)
	v_mfma_f32_16x16x32_bf16 v[128:131], v[132:135], v[188:191], v[128:131]
	v_mfma_f32_16x16x32_bf16 v[120:123], v[150:153], v[188:191], v[120:123]
	v_mfma_f32_16x16x32_bf16 v[112:115], v[132:135], v[196:199], v[112:115]
	v_mfma_f32_16x16x32_bf16 v[104:107], v[150:153], v[196:199], v[104:107]
	v_mfma_f32_16x16x32_bf16 v[96:99], v[132:135], v[204:207], v[96:99]
	v_mfma_f32_16x16x32_bf16 v[88:91], v[150:153], v[204:207], v[88:91]
	v_mfma_f32_16x16x32_bf16 v[80:83], v[132:135], v[212:215], v[80:83]
	v_mfma_f32_16x16x32_bf16 v[72:75], v[150:153], v[212:215], v[72:75]
	v_mfma_f32_16x16x32_bf16 v[128:131], v[146:149], v[192:195], v[128:131]
	v_mfma_f32_16x16x32_bf16 v[120:123], v[154:157], v[192:195], v[120:123]
	v_mfma_f32_16x16x32_bf16 v[112:115], v[146:149], v[200:203], v[112:115]
	v_mfma_f32_16x16x32_bf16 v[104:107], v[154:157], v[200:203], v[104:107]
	v_mfma_f32_16x16x32_bf16 v[96:99], v[146:149], v[208:211], v[96:99]
	v_mfma_f32_16x16x32_bf16 v[88:91], v[154:157], v[208:211], v[88:91]
	v_mfma_f32_16x16x32_bf16 v[80:83], v[146:149], v[216:219], v[80:83]
	v_mfma_f32_16x16x32_bf16 v[72:75], v[154:157], v[216:219], v[72:75]
	v_mfma_f32_16x16x32_bf16 v[124:127], v[158:161], v[188:191], v[124:127]
	v_mfma_f32_16x16x32_bf16 v[116:119], v[170:173], v[188:191], v[116:119]
	v_mfma_f32_16x16x32_bf16 v[108:111], v[158:161], v[196:199], v[108:111]
	v_mfma_f32_16x16x32_bf16 v[100:103], v[170:173], v[196:199], v[100:103]
	v_mfma_f32_16x16x32_bf16 v[92:95], v[158:161], v[204:207], v[92:95]
	v_mfma_f32_16x16x32_bf16 v[84:87], v[170:173], v[204:207], v[84:87]
	v_mfma_f32_16x16x32_bf16 v[76:79], v[158:161], v[212:215], v[76:79]
	v_mfma_f32_16x16x32_bf16 v[68:71], v[170:173], v[212:215], v[68:71]
	v_mfma_f32_16x16x32_bf16 v[124:127], v[166:169], v[192:195], v[124:127]
	v_mfma_f32_16x16x32_bf16 v[116:119], v[174:177], v[192:195], v[116:119]
	v_mfma_f32_16x16x32_bf16 v[108:111], v[166:169], v[200:203], v[108:111]
	v_mfma_f32_16x16x32_bf16 v[100:103], v[174:177], v[200:203], v[100:103]
	v_mfma_f32_16x16x32_bf16 v[92:95], v[166:169], v[208:211], v[92:95]
	v_mfma_f32_16x16x32_bf16 v[84:87], v[174:177], v[208:211], v[84:87]
	v_mfma_f32_16x16x32_bf16 v[76:79], v[166:169], v[216:219], v[76:79]
	v_mfma_f32_16x16x32_bf16 v[68:71], v[174:177], v[216:219], v[68:71]
	s_barrier
	s_mov_b32 m0, s45
	v_lshl_add_u64 v[178:179], v[178:179], 0, s[96:97]
	s_add_u32 s26, s26, 0x40080
	ds_read_b128 v[188:191], v165 offset:49152
	ds_read_b128 v[192:195], v165 offset:50176
	ds_read_b128 v[196:199], v165 offset:51200
	ds_read_b128 v[200:203], v165 offset:52224
	ds_read_b128 v[204:207], v165 offset:53248
	ds_read_b128 v[208:211], v165 offset:54272
	ds_read_b128 v[212:215], v165 offset:55296
	ds_read_b128 v[216:219], v165 offset:56320
	global_load_lds_dwordx4 v[178:179], off
	v_lshl_add_u64 v[178:179], v[220:221], 0, s[96:97]
	s_mov_b32 m0, s46
	s_addc_u32 s27, s27, 0
	global_load_lds_dwordx4 v[178:179], off
	s_mov_b32 m0, s50
	v_lshl_add_u64 v[178:179], s[26:27], 0, v[2:3]
	global_load_lds_dwordx4 v[178:179], off
	s_mov_b32 m0, s51
	v_lshl_add_u64 v[178:179], s[26:27], 0, v[0:1]
	global_load_lds_dwordx4 v[178:179], off
	s_mov_b32 m0, s47
	v_lshl_add_u64 v[178:179], v[222:223], 0, s[96:97]
	global_load_lds_dwordx4 v[178:179], off
	s_mov_b32 m0, s48
	v_lshl_add_u64 v[178:179], v[224:225], 0, s[96:97]
	global_load_lds_dwordx4 v[178:179], off
	s_waitcnt vmcnt(8)
	s_waitcnt lgkmcnt(0)
	s_barrier
	s_waitcnt lgkmcnt(0)
	v_mfma_f32_16x16x32_bf16 v[64:67], v[132:135], v[188:191], v[64:67]
	v_mfma_f32_16x16x32_bf16 v[56:59], v[150:153], v[188:191], v[56:59]
	v_mfma_f32_16x16x32_bf16 v[48:51], v[132:135], v[196:199], v[48:51]
	v_mfma_f32_16x16x32_bf16 v[40:43], v[150:153], v[196:199], v[40:43]
	v_mfma_f32_16x16x32_bf16 v[32:35], v[132:135], v[204:207], v[32:35]
	v_mfma_f32_16x16x32_bf16 v[24:27], v[150:153], v[204:207], v[24:27]
	v_mfma_f32_16x16x32_bf16 v[16:19], v[132:135], v[212:215], v[16:19]
	v_mfma_f32_16x16x32_bf16 v[8:11], v[150:153], v[212:215], v[8:11]
	v_mfma_f32_16x16x32_bf16 v[64:67], v[146:149], v[192:195], v[64:67]
	v_mfma_f32_16x16x32_bf16 v[56:59], v[154:157], v[192:195], v[56:59]
	v_mfma_f32_16x16x32_bf16 v[48:51], v[146:149], v[200:203], v[48:51]
	v_mfma_f32_16x16x32_bf16 v[40:43], v[154:157], v[200:203], v[40:43]
	v_mfma_f32_16x16x32_bf16 v[32:35], v[146:149], v[208:211], v[32:35]
	v_mfma_f32_16x16x32_bf16 v[24:27], v[154:157], v[208:211], v[24:27]
	v_mfma_f32_16x16x32_bf16 v[16:19], v[146:149], v[216:219], v[16:19]
	v_mfma_f32_16x16x32_bf16 v[8:11], v[154:157], v[216:219], v[8:11]
	v_mfma_f32_16x16x32_bf16 v[60:63], v[158:161], v[188:191], v[60:63]
	v_mfma_f32_16x16x32_bf16 v[52:55], v[170:173], v[188:191], v[52:55]
	v_mfma_f32_16x16x32_bf16 v[44:47], v[158:161], v[196:199], v[44:47]
	v_mfma_f32_16x16x32_bf16 v[36:39], v[170:173], v[196:199], v[36:39]
	v_mfma_f32_16x16x32_bf16 v[28:31], v[158:161], v[204:207], v[28:31]
	v_mfma_f32_16x16x32_bf16 v[20:23], v[170:173], v[204:207], v[20:23]
	v_mfma_f32_16x16x32_bf16 v[12:15], v[158:161], v[212:215], v[12:15]
	v_mfma_f32_16x16x32_bf16 v[4:7], v[170:173], v[212:215], v[4:7]
	v_mfma_f32_16x16x32_bf16 v[60:63], v[166:169], v[192:195], v[60:63]
	v_mfma_f32_16x16x32_bf16 v[52:55], v[174:177], v[192:195], v[52:55]
	v_mfma_f32_16x16x32_bf16 v[44:47], v[166:169], v[200:203], v[44:47]
	v_mfma_f32_16x16x32_bf16 v[36:39], v[174:177], v[200:203], v[36:39]
	v_mfma_f32_16x16x32_bf16 v[28:31], v[166:169], v[208:211], v[28:31]
	v_mfma_f32_16x16x32_bf16 v[20:23], v[174:177], v[208:211], v[20:23]
	v_mfma_f32_16x16x32_bf16 v[12:15], v[166:169], v[216:219], v[12:15]
	v_mfma_f32_16x16x32_bf16 v[4:7], v[174:177], v[216:219], v[4:7]
	s_barrier
	s_add_i32 s57, s57, 2
	s_add_u32 s24, s24, 0x100
	s_addc_u32 s25, s25, 0
	s_add_u32 s55, s55, 0x100
	s_addc_u32 s56, s56, 0
; #define PG8_STAGE(bufoff, gbase, voff) do { _Pragma("unroll") for (int _i = 0; _i < 2; ++_i) \
;         __builtin_amdgcn_global_load_lds((const unsigned*)((const char*)(gbase) + (voff)[_i]), (PG8_LAS unsigned*)(lds + (bufoff) + ldsw + _i * 8192), 16, 0, 0); } while (0)
; #define PG8_LDA(dst, b, h) do { _Pragma("unroll") for (int m = 0; m < 4; ++m) _Pragma("unroll") for (int k = 0; k < 2; ++k) dst[m][k] = *(const PG8_LAS bf16x8*)(lds + PG8_SA(b, h) + aoff + m * 2048 + k * 1024); } while (0)
; #define PG8_LDB(dst, b, h) do { _Pragma("unroll") for (int n = 0; n < 2; ++n) _Pragma("unroll") for (int k = 0; k < 2; ++k) dst[n][k] = *(const PG8_LAS bf16x8*)(lds + PG8_SB(b, h) + boff + n * 2048 + k * 1024); } while (0)
; #define PG8_MMA(ai, bj, At, Bt) do { __builtin_amdgcn_s_setprio(1); _Pragma("unroll") for (int m = 0; m < 4; ++m) _Pragma("unroll") for (int n = 0; n < 2; ++n) _Pragma("unroll") for (int k = 0; k < 2; ++k) \
;         acc[ai][bj][m][n] = __builtin_amdgcn_mfma_f32_16x16x32_bf16(Bt[n][k], At[m][k], acc[ai][bj][m][n], 0, 0, 0); __builtin_amdgcn_s_setprio(0); } while (0)
; #define PG8_WAIT_V(n) asm volatile("s_waitcnt vmcnt(" #n ")" ::: "memory")
; #define PG8_WAIT_L(n) asm volatile("s_waitcnt lgkmcnt(" #n ")" ::: "memory")
; #define PG8_BAR __builtin_amdgcn_s_barrier()
; #define PG8_SCHED __builtin_amdgcn_sched_barrier(0)
; template <class Epi, class Sched, bool ALIGN_EPI = false, bool SP2 = false>
; __device__ __forceinline__ void gemm_phase(PG8_LAS unsigned char* lds, const Gemm g, const Sched& S, const Epi& E, const int tid_) {
;     ...
;             PG8_LDB(B0, 0, 0); PG8_LDB(B1, 0, 1); PG8_SCHED; PG8_LDA(At, 0, 0); PG8_STAGE(PG8_SA(1, 1), a1 + hstep, voffA);
;             PG8_WAIT_V(8); PG8_WAIT_L(0); PG8_BAR; PG8_MMA(0, 0, At, B0); PG8_MMA(0, 1, At, B1); PG8_BAR; PG8_SCHED;
;             PG8_LDA(At, 0, 1); PG8_STAGE(PG8_SB(0, 0), b2, voffB); PG8_STAGE(PG8_SB(0, 1), b2 + hstepB, voffB); PG8_STAGE(PG8_SA(0, 0), a2, voffA);
;             PG8_WAIT_V(8); PG8_WAIT_L(0); PG8_BAR; PG8_MMA(1, 0, At, B0); PG8_MMA(1, 1, At, B1); PG8_BAR; PG8_SCHED;
.LBB0_24:
	v_add_u32_e32 v154, s23, v163
	v_add_u32_e32 v174, s37, v163
	ds_read_b128 v[132:135], v154
	ds_read_b128 v[146:149], v154 offset:1024
	ds_read_b128 v[150:153], v154 offset:2048
	ds_read_b128 v[154:157], v154 offset:3072
	ds_read_b128 v[158:161], v174
	ds_read_b128 v[166:169], v174 offset:1024
	ds_read_b128 v[170:173], v174 offset:2048
	ds_read_b128 v[174:177], v174 offset:3072
	s_add_u32 s26, s24, 0xfffc0080
	s_addc_u32 s27, s25, -1
	s_cmp_eq_u32 s57, 12
	s_cselect_b32 s29, s2, s27
	s_cselect_b32 s28, s3, s26
	s_cselect_b32 s27, s15, s56
	s_cselect_b32 s26, s17, s55
	v_lshl_add_u64 v[178:179], s[24:25], 0, v[142:143]
	s_add_i32 m0, s40, 0xc000
	ds_read_b128 v[188:191], v165
	ds_read_b128 v[192:195], v165 offset:1024
	ds_read_b128 v[196:199], v165 offset:2048
	ds_read_b128 v[200:203], v165 offset:3072
	ds_read_b128 v[204:207], v165 offset:4096
	ds_read_b128 v[208:211], v165 offset:5120
	ds_read_b128 v[212:215], v165 offset:6144
	ds_read_b128 v[216:219], v165 offset:7168
	global_load_lds_dwordx4 v[178:179], off
	v_lshl_add_u64 v[178:179], s[24:25], 0, v[144:145]
	s_add_i32 m0, s40, 0xe000
	s_nop 0
	global_load_lds_dwordx4 v[178:179], off
	s_waitcnt vmcnt(8)
	s_waitcnt lgkmcnt(0)
	s_barrier
	s_waitcnt lgkmcnt(0)
	v_mfma_f32_16x16x32_bf16 v[128:131], v[132:135], v[188:191], v[128:131]
	v_mfma_f32_16x16x32_bf16 v[120:123], v[150:153], v[188:191], v[120:123]
	v_mfma_f32_16x16x32_bf16 v[112:115], v[132:135], v[196:199], v[112:115]
	v_mfma_f32_16x16x32_bf16 v[104:107], v[150:153], v[196:199], v[104:107]
	v_mfma_f32_16x16x32_bf16 v[96:99], v[132:135], v[204:207], v[96:99]
	v_mfma_f32_16x16x32_bf16 v[88:91], v[150:153], v[204:207], v[88:91]
	v_mfma_f32_16x16x32_bf16 v[80:83], v[132:135], v[212:215], v[80:83]
	v_mfma_f32_16x16x32_bf16 v[72:75], v[150:153], v[212:215], v[72:75]
	v_mfma_f32_16x16x32_bf16 v[128:131], v[146:149], v[192:195], v[128:131]
	v_mfma_f32_16x16x32_bf16 v[120:123], v[154:157], v[192:195], v[120:123]
	v_mfma_f32_16x16x32_bf16 v[112:115], v[146:149], v[200:203], v[112:115]
	v_mfma_f32_16x16x32_bf16 v[104:107], v[154:157], v[200:203], v[104:107]
	v_mfma_f32_16x16x32_bf16 v[96:99], v[146:149], v[208:211], v[96:99]
	v_mfma_f32_16x16x32_bf16 v[88:91], v[154:157], v[208:211], v[88:91]
	v_mfma_f32_16x16x32_bf16 v[80:83], v[146:149], v[216:219], v[80:83]
	v_mfma_f32_16x16x32_bf16 v[72:75], v[154:157], v[216:219], v[72:75]
	v_mfma_f32_16x16x32_bf16 v[124:127], v[158:161], v[188:191], v[124:127]
	v_mfma_f32_16x16x32_bf16 v[116:119], v[170:173], v[188:191], v[116:119]
	v_mfma_f32_16x16x32_bf16 v[108:111], v[158:161], v[196:199], v[108:111]
	v_mfma_f32_16x16x32_bf16 v[100:103], v[170:173], v[196:199], v[100:103]
	v_mfma_f32_16x16x32_bf16 v[92:95], v[158:161], v[204:207], v[92:95]
	v_mfma_f32_16x16x32_bf16 v[84:87], v[170:173], v[204:207], v[84:87]
	v_mfma_f32_16x16x32_bf16 v[76:79], v[158:161], v[212:215], v[76:79]
	v_mfma_f32_16x16x32_bf16 v[68:71], v[170:173], v[212:215], v[68:71]
	v_mfma_f32_16x16x32_bf16 v[124:127], v[166:169], v[192:195], v[124:127]
	v_mfma_f32_16x16x32_bf16 v[116:119], v[174:177], v[192:195], v[116:119]
	v_mfma_f32_16x16x32_bf16 v[108:111], v[166:169], v[200:203], v[108:111]
	v_mfma_f32_16x16x32_bf16 v[100:103], v[174:177], v[200:203], v[100:103]
	v_mfma_f32_16x16x32_bf16 v[92:95], v[166:169], v[208:211], v[92:95]
	v_mfma_f32_16x16x32_bf16 v[84:87], v[174:177], v[208:211], v[84:87]
	v_mfma_f32_16x16x32_bf16 v[76:79], v[166:169], v[216:219], v[76:79]
	v_mfma_f32_16x16x32_bf16 v[68:71], v[174:177], v[216:219], v[68:71]
	s_barrier
	s_mov_b32 m0, s35
	v_lshl_add_u64 v[178:179], s[26:27], 0, v[2:3]
	s_add_u32 s58, s26, 0x40000
	ds_read_b128 v[188:191], v165 offset:16384
	ds_read_b128 v[192:195], v165 offset:17408
	ds_read_b128 v[196:199], v165 offset:18432
	ds_read_b128 v[200:203], v165 offset:19456
	ds_read_b128 v[204:207], v165 offset:20480
	ds_read_b128 v[208:211], v165 offset:21504
	ds_read_b128 v[212:215], v165 offset:22528
	ds_read_b128 v[216:219], v165 offset:23552
	global_load_lds_dwordx4 v[178:179], off
	v_lshl_add_u64 v[220:221], s[26:27], 0, v[0:1]
	s_mov_b32 m0, s36
	s_addc_u32 s59, s27, 0
	global_load_lds_dwordx4 v[220:221], off
	v_lshl_add_u64 v[222:223], s[58:59], 0, v[2:3]
	s_mov_b32 m0, s38
	v_lshl_add_u64 v[224:225], s[28:29], 0, v[136:137]
	global_load_lds_dwordx4 v[222:223], off
	s_mov_b32 m0, s39
	v_lshl_add_u64 v[222:223], s[58:59], 0, v[0:1]
	global_load_lds_dwordx4 v[222:223], off
	s_mov_b32 m0, s40
	v_lshl_add_u64 v[222:223], s[28:29], 0, v[138:139]
	global_load_lds_dwordx4 v[222:223], off
	s_mov_b32 m0, s41
	s_nop 0
	global_load_lds_dwordx4 v[224:225], off
	s_waitcnt vmcnt(8)
	s_waitcnt lgkmcnt(0)
	s_barrier
; #define PG8_STAGE(bufoff, gbase, voff) do { _Pragma("unroll") for (int _i = 0; _i < 2; ++_i) \
;         __builtin_amdgcn_global_load_lds((const unsigned*)((const char*)(gbase) + (voff)[_i]), (PG8_LAS unsigned*)(lds + (bufoff) + ldsw + _i * 8192), 16, 0, 0); } while (0)
; #define PG8_LDA(dst, b, h) do { _Pragma("unroll") for (int m = 0; m < 4; ++m) _Pragma("unroll") for (int k = 0; k < 2; ++k) dst[m][k] = *(const PG8_LAS bf16x8*)(lds + PG8_SA(b, h) + aoff + m * 2048 + k * 1024); } while (0)
; #define PG8_LDB(dst, b, h) do { _Pragma("unroll") for (int n = 0; n < 2; ++n) _Pragma("unroll") for (int k = 0; k < 2; ++k) dst[n][k] = *(const PG8_LAS bf16x8*)(lds + PG8_SB(b, h) + boff + n * 2048 + k * 1024); } while (0)
; #define PG8_MMA(ai, bj, At, Bt) do { __builtin_amdgcn_s_setprio(1); _Pragma("unroll") for (int m = 0; m < 4; ++m) _Pragma("unroll") for (int n = 0; n < 2; ++n) _Pragma("unroll") for (int k = 0; k < 2; ++k) \
;         acc[ai][bj][m][n] = __builtin_amdgcn_mfma_f32_16x16x32_bf16(Bt[n][k], At[m][k], acc[ai][bj][m][n], 0, 0, 0); __builtin_amdgcn_s_setprio(0); } while (0)
; #define PG8_WAIT_V(n) asm volatile("s_waitcnt vmcnt(" #n ")" ::: "memory")
; #define PG8_WAIT_L(n) asm volatile("s_waitcnt lgkmcnt(" #n ")" ::: "memory")
; #define PG8_BAR __builtin_amdgcn_s_barrier()
; #define PG8_SCHED __builtin_amdgcn_sched_barrier(0)
; template <class Epi, class Sched, bool ALIGN_EPI = false, bool SP2 = false>
; __device__ __forceinline__ void gemm_phase(PG8_LAS unsigned char* lds, const Gemm g, const Sched& S, const Epi& E, const int tid_) {
;     ...
;             PG8_WAIT_V(8); PG8_WAIT_L(0); PG8_BAR; PG8_MMA(1, 0, At, B0); PG8_MMA(1, 1, At, B1); PG8_BAR; PG8_SCHED;
;             PG8_LDB(B0, 1, 0); PG8_LDB(B1, 1, 1); PG8_SCHED; PG8_LDA(At, 1, 0); PG8_STAGE(PG8_SA(0, 1), a2 + hstep, voffA);
;             PG8_WAIT_V(8); PG8_WAIT_L(0); PG8_BAR; PG8_MMA(0, 0, At, B0); PG8_MMA(0, 1, At, B1); PG8_BAR; PG8_SCHED;
	s_waitcnt lgkmcnt(0)
	v_mfma_f32_16x16x32_bf16 v[64:67], v[132:135], v[188:191], v[64:67]
	v_mfma_f32_16x16x32_bf16 v[56:59], v[150:153], v[188:191], v[56:59]
	v_mfma_f32_16x16x32_bf16 v[48:51], v[132:135], v[196:199], v[48:51]
	v_mfma_f32_16x16x32_bf16 v[40:43], v[150:153], v[196:199], v[40:43]
	v_mfma_f32_16x16x32_bf16 v[32:35], v[132:135], v[204:207], v[32:35]
	v_mfma_f32_16x16x32_bf16 v[24:27], v[150:153], v[204:207], v[24:27]
	v_mfma_f32_16x16x32_bf16 v[16:19], v[132:135], v[212:215], v[16:19]
	v_mfma_f32_16x16x32_bf16 v[8:11], v[150:153], v[212:215], v[8:11]
	v_mfma_f32_16x16x32_bf16 v[64:67], v[146:149], v[192:195], v[64:67]
	v_mfma_f32_16x16x32_bf16 v[56:59], v[154:157], v[192:195], v[56:59]
	v_mfma_f32_16x16x32_bf16 v[48:51], v[146:149], v[200:203], v[48:51]
	v_mfma_f32_16x16x32_bf16 v[40:43], v[154:157], v[200:203], v[40:43]
	v_mfma_f32_16x16x32_bf16 v[32:35], v[146:149], v[208:211], v[32:35]
	v_mfma_f32_16x16x32_bf16 v[24:27], v[154:157], v[208:211], v[24:27]
	v_mfma_f32_16x16x32_bf16 v[16:19], v[146:149], v[216:219], v[16:19]
	v_mfma_f32_16x16x32_bf16 v[8:11], v[154:157], v[216:219], v[8:11]
	v_mfma_f32_16x16x32_bf16 v[60:63], v[158:161], v[188:191], v[60:63]
	v_mfma_f32_16x16x32_bf16 v[52:55], v[170:173], v[188:191], v[52:55]
	v_mfma_f32_16x16x32_bf16 v[44:47], v[158:161], v[196:199], v[44:47]
	v_mfma_f32_16x16x32_bf16 v[36:39], v[170:173], v[196:199], v[36:39]
	v_mfma_f32_16x16x32_bf16 v[28:31], v[158:161], v[204:207], v[28:31]
	v_mfma_f32_16x16x32_bf16 v[20:23], v[170:173], v[204:207], v[20:23]
	v_mfma_f32_16x16x32_bf16 v[12:15], v[158:161], v[212:215], v[12:15]
	v_mfma_f32_16x16x32_bf16 v[4:7], v[170:173], v[212:215], v[4:7]
	v_mfma_f32_16x16x32_bf16 v[60:63], v[166:169], v[192:195], v[60:63]
	v_mfma_f32_16x16x32_bf16 v[52:55], v[174:177], v[192:195], v[52:55]
	v_mfma_f32_16x16x32_bf16 v[44:47], v[166:169], v[200:203], v[44:47]
	v_mfma_f32_16x16x32_bf16 v[36:39], v[174:177], v[200:203], v[36:39]
	v_mfma_f32_16x16x32_bf16 v[28:31], v[166:169], v[208:211], v[28:31]
	v_mfma_f32_16x16x32_bf16 v[20:23], v[174:177], v[208:211], v[20:23]
	v_mfma_f32_16x16x32_bf16 v[12:15], v[166:169], v[216:219], v[12:15]
	v_mfma_f32_16x16x32_bf16 v[4:7], v[174:177], v[216:219], v[4:7]
	s_barrier
	v_add_u32_e32 v154, s44, v163
	v_add_u32_e32 v174, s49, v163
	ds_read_b128 v[132:135], v154
	ds_read_b128 v[146:149], v154 offset:1024
	ds_read_b128 v[150:153], v154 offset:2048
	ds_read_b128 v[154:157], v154 offset:3072
	ds_read_b128 v[158:161], v174
	ds_read_b128 v[166:169], v174 offset:1024
	ds_read_b128 v[170:173], v174 offset:2048
	ds_read_b128 v[174:177], v174 offset:3072
	s_add_u32 s28, s28, 0x40000
	s_addc_u32 s29, s29, 0
	s_mov_b32 m0, s42
	v_lshl_add_u64 v[226:227], s[28:29], 0, v[138:139]
	ds_read_b128 v[188:191], v165 offset:32768
	ds_read_b128 v[192:195], v165 offset:33792
	ds_read_b128 v[196:199], v165 offset:34816
	ds_read_b128 v[200:203], v165 offset:35840
	ds_read_b128 v[204:207], v165 offset:36864
	ds_read_b128 v[208:211], v165 offset:37888
	ds_read_b128 v[212:215], v165 offset:38912
	ds_read_b128 v[216:219], v165 offset:39936
	global_load_lds_dwordx4 v[226:227], off
	s_mov_b32 m0, s43
	v_lshl_add_u64 v[226:227], s[28:29], 0, v[136:137]
	global_load_lds_dwordx4 v[226:227], off
	s_waitcnt vmcnt(8)
	s_waitcnt lgkmcnt(0)
	s_barrier
	s_waitcnt lgkmcnt(0)
	v_mfma_f32_16x16x32_bf16 v[128:131], v[132:135], v[188:191], v[128:131]
	v_mfma_f32_16x16x32_bf16 v[120:123], v[150:153], v[188:191], v[120:123]
	v_mfma_f32_16x16x32_bf16 v[112:115], v[132:135], v[196:199], v[112:115]
	v_mfma_f32_16x16x32_bf16 v[104:107], v[150:153], v[196:199], v[104:107]
	v_mfma_f32_16x16x32_bf16 v[96:99], v[132:135], v[204:207], v[96:99]
	v_mfma_f32_16x16x32_bf16 v[88:91], v[150:153], v[204:207], v[88:91]
	v_mfma_f32_16x16x32_bf16 v[80:83], v[132:135], v[212:215], v[80:83]
	v_mfma_f32_16x16x32_bf16 v[72:75], v[150:153], v[212:215], v[72:75]
	v_mfma_f32_16x16x32_bf16 v[128:131], v[146:149], v[192:195], v[128:131]
	v_mfma_f32_16x16x32_bf16 v[120:123], v[154:157], v[192:195], v[120:123]
	v_mfma_f32_16x16x32_bf16 v[112:115], v[146:149], v[200:203], v[112:115]
	v_mfma_f32_16x16x32_bf16 v[104:107], v[154:157], v[200:203], v[104:107]
	v_mfma_f32_16x16x32_bf16 v[96:99], v[146:149], v[208:211], v[96:99]
	v_mfma_f32_16x16x32_bf16 v[88:91], v[154:157], v[208:211], v[88:91]
	v_mfma_f32_16x16x32_bf16 v[80:83], v[146:149], v[216:219], v[80:83]
	v_mfma_f32_16x16x32_bf16 v[72:75], v[154:157], v[216:219], v[72:75]
	v_mfma_f32_16x16x32_bf16 v[124:127], v[158:161], v[188:191], v[124:127]
	v_mfma_f32_16x16x32_bf16 v[116:119], v[170:173], v[188:191], v[116:119]
	v_mfma_f32_16x16x32_bf16 v[108:111], v[158:161], v[196:199], v[108:111]
	v_mfma_f32_16x16x32_bf16 v[100:103], v[170:173], v[196:199], v[100:103]
	v_mfma_f32_16x16x32_bf16 v[92:95], v[158:161], v[204:207], v[92:95]
	v_mfma_f32_16x16x32_bf16 v[84:87], v[170:173], v[204:207], v[84:87]
	v_mfma_f32_16x16x32_bf16 v[76:79], v[158:161], v[212:215], v[76:79]
	v_mfma_f32_16x16x32_bf16 v[68:71], v[170:173], v[212:215], v[68:71]
	v_mfma_f32_16x16x32_bf16 v[124:127], v[166:169], v[192:195], v[124:127]
	v_mfma_f32_16x16x32_bf16 v[116:119], v[174:177], v[192:195], v[116:119]
	v_mfma_f32_16x16x32_bf16 v[108:111], v[166:169], v[200:203], v[108:111]
	v_mfma_f32_16x16x32_bf16 v[100:103], v[174:177], v[200:203], v[100:103]
	v_mfma_f32_16x16x32_bf16 v[92:95], v[166:169], v[208:211], v[92:95]
	v_mfma_f32_16x16x32_bf16 v[84:87], v[174:177], v[208:211], v[84:87]
	v_mfma_f32_16x16x32_bf16 v[76:79], v[166:169], v[216:219], v[76:79]
	v_mfma_f32_16x16x32_bf16 v[68:71], v[174:177], v[216:219], v[68:71]
	s_barrier
; #define PG8_STAGE(bufoff, gbase, voff) do { _Pragma("unroll") for (int _i = 0; _i < 2; ++_i) \
;         __builtin_amdgcn_global_load_lds((const unsigned*)((const char*)(gbase) + (voff)[_i]), (PG8_LAS unsigned*)(lds + (bufoff) + ldsw + _i * 8192), 16, 0, 0); } while (0)
; #define PG8_LDA(dst, b, h) do { _Pragma("unroll") for (int m = 0; m < 4; ++m) _Pragma("unroll") for (int k = 0; k < 2; ++k) dst[m][k] = *(const PG8_LAS bf16x8*)(lds + PG8_SA(b, h) + aoff + m * 2048 + k * 1024); } while (0)
; #define PG8_MMA(ai, bj, At, Bt) do { __builtin_amdgcn_s_setprio(1); _Pragma("unroll") for (int m = 0; m < 4; ++m) _Pragma("unroll") for (int n = 0; n < 2; ++n) _Pragma("unroll") for (int k = 0; k < 2; ++k) \
;         acc[ai][bj][m][n] = __builtin_amdgcn_mfma_f32_16x16x32_bf16(Bt[n][k], At[m][k], acc[ai][bj][m][n], 0, 0, 0); __builtin_amdgcn_s_setprio(0); } while (0)
; #define PG8_WAIT_V(n) asm volatile("s_waitcnt vmcnt(" #n ")" ::: "memory")
; #define PG8_WAIT_L(n) asm volatile("s_waitcnt lgkmcnt(" #n ")" ::: "memory")
; #define PG8_BAR __builtin_amdgcn_s_barrier()
; #define PG8_SCHED __builtin_amdgcn_sched_barrier(0)
; template <class Epi, class Sched, bool ALIGN_EPI = false, bool SP2 = false>
; __device__ __forceinline__ void gemm_phase(PG8_LAS unsigned char* lds, const Gemm g, const Sched& S, const Epi& E, const int tid_) {
;     ...
;             PG8_LDA(At, 1, 1); PG8_STAGE(PG8_SB(1, 0), b3, voffB); PG8_STAGE(PG8_SB(1, 1), b3 + hstepB, voffB); PG8_STAGE(PG8_SA(1, 0), a3, voffA);
;             PG8_WAIT_V(8); PG8_WAIT_L(0); PG8_BAR; PG8_MMA(1, 0, At, B0); PG8_MMA(1, 1, At, B1); PG8_BAR; PG8_SCHED;
	s_mov_b32 m0, s45
	v_lshl_add_u64 v[178:179], v[178:179], 0, s[96:97]
	s_add_u32 s26, s26, 0x40080
	ds_read_b128 v[188:191], v165 offset:49152
	ds_read_b128 v[192:195], v165 offset:50176
	ds_read_b128 v[196:199], v165 offset:51200
	ds_read_b128 v[200:203], v165 offset:52224
	ds_read_b128 v[204:207], v165 offset:53248
	ds_read_b128 v[208:211], v165 offset:54272
	ds_read_b128 v[212:215], v165 offset:55296
	ds_read_b128 v[216:219], v165 offset:56320
	global_load_lds_dwordx4 v[178:179], off
	v_lshl_add_u64 v[178:179], v[220:221], 0, s[96:97]
	s_mov_b32 m0, s46
	s_addc_u32 s27, s27, 0
	global_load_lds_dwordx4 v[178:179], off
	s_mov_b32 m0, s50
	v_lshl_add_u64 v[178:179], s[26:27], 0, v[2:3]
	global_load_lds_dwordx4 v[178:179], off
	s_mov_b32 m0, s51
	v_lshl_add_u64 v[178:179], s[26:27], 0, v[0:1]
	global_load_lds_dwordx4 v[178:179], off
	s_mov_b32 m0, s47
	v_lshl_add_u64 v[178:179], v[222:223], 0, s[96:97]
	global_load_lds_dwordx4 v[178:179], off
	s_mov_b32 m0, s48
	v_lshl_add_u64 v[178:179], v[224:225], 0, s[96:97]
	global_load_lds_dwordx4 v[178:179], off
	s_waitcnt vmcnt(8)
	s_waitcnt lgkmcnt(0)
	s_barrier
	s_waitcnt lgkmcnt(0)
	v_mfma_f32_16x16x32_bf16 v[64:67], v[132:135], v[188:191], v[64:67]
	v_mfma_f32_16x16x32_bf16 v[56:59], v[150:153], v[188:191], v[56:59]
	v_mfma_f32_16x16x32_bf16 v[48:51], v[132:135], v[196:199], v[48:51]
	v_mfma_f32_16x16x32_bf16 v[40:43], v[150:153], v[196:199], v[40:43]
	v_mfma_f32_16x16x32_bf16 v[32:35], v[132:135], v[204:207], v[32:35]
	v_mfma_f32_16x16x32_bf16 v[24:27], v[150:153], v[204:207], v[24:27]
	v_mfma_f32_16x16x32_bf16 v[16:19], v[132:135], v[212:215], v[16:19]
	v_mfma_f32_16x16x32_bf16 v[8:11], v[150:153], v[212:215], v[8:11]
	v_mfma_f32_16x16x32_bf16 v[64:67], v[146:149], v[192:195], v[64:67]
	v_mfma_f32_16x16x32_bf16 v[56:59], v[154:157], v[192:195], v[56:59]
	v_mfma_f32_16x16x32_bf16 v[48:51], v[146:149], v[200:203], v[48:51]
	v_mfma_f32_16x16x32_bf16 v[40:43], v[154:157], v[200:203], v[40:43]
	v_mfma_f32_16x16x32_bf16 v[32:35], v[146:149], v[208:211], v[32:35]
	v_mfma_f32_16x16x32_bf16 v[24:27], v[154:157], v[208:211], v[24:27]
	v_mfma_f32_16x16x32_bf16 v[16:19], v[146:149], v[216:219], v[16:19]
	v_mfma_f32_16x16x32_bf16 v[8:11], v[154:157], v[216:219], v[8:11]
	v_mfma_f32_16x16x32_bf16 v[60:63], v[158:161], v[188:191], v[60:63]
	v_mfma_f32_16x16x32_bf16 v[52:55], v[170:173], v[188:191], v[52:55]
	v_mfma_f32_16x16x32_bf16 v[44:47], v[158:161], v[196:199], v[44:47]
	v_mfma_f32_16x16x32_bf16 v[36:39], v[170:173], v[196:199], v[36:39]
	v_mfma_f32_16x16x32_bf16 v[28:31], v[158:161], v[204:207], v[28:31]
	v_mfma_f32_16x16x32_bf16 v[20:23], v[170:173], v[204:207], v[20:23]
	v_mfma_f32_16x16x32_bf16 v[12:15], v[158:161], v[212:215], v[12:15]
	v_mfma_f32_16x16x32_bf16 v[4:7], v[170:173], v[212:215], v[4:7]
	v_mfma_f32_16x16x32_bf16 v[60:63], v[166:169], v[192:195], v[60:63]
	v_mfma_f32_16x16x32_bf16 v[52:55], v[174:177], v[192:195], v[52:55]
	v_mfma_f32_16x16x32_bf16 v[44:47], v[166:169], v[200:203], v[44:47]
	v_mfma_f32_16x16x32_bf16 v[36:39], v[174:177], v[200:203], v[36:39]
	v_mfma_f32_16x16x32_bf16 v[28:31], v[166:169], v[208:211], v[28:31]
	v_mfma_f32_16x16x32_bf16 v[20:23], v[174:177], v[208:211], v[20:23]
	v_mfma_f32_16x16x32_bf16 v[12:15], v[166:169], v[216:219], v[12:15]
	v_mfma_f32_16x16x32_bf16 v[4:7], v[174:177], v[216:219], v[4:7]
	s_barrier
	s_add_i32 s57, s57, 2
	s_add_u32 s24, s24, 0x100
	s_addc_u32 s25, s25, 0
	s_add_u32 s55, s55, 0x100
	s_addc_u32 s56, s56, 0
	s_cmp_gt_u32 s57, 13
	s_cbranch_scc0 .LBB0_24
	s_and_b64 vcc, exec, s[12:13]
	s_cbranch_vccz .LBB0_27
	s_barrier

; #define PG8_STAGE(bufoff, gbase, voff) do { _Pragma("unroll") for (int _i = 0; _i < 2; ++_i) \
;         __builtin_amdgcn_global_load_lds((const unsigned*)((const char*)(gbase) + (voff)[_i]), (PG8_LAS unsigned*)(lds + (bufoff) + ldsw + _i * 8192), 16, 0, 0); } while (0)
; #define PG8_LDA(dst, b, h) do { _Pragma("unroll") for (int m = 0; m < 4; ++m) _Pragma("unroll") for (int k = 0; k < 2; ++k) dst[m][k] = *(const PG8_LAS bf16x8*)(lds + PG8_SA(b, h) + aoff + m * 2048 + k * 1024); } while (0)
; #define PG8_LDB(dst, b, h) do { _Pragma("unroll") for (int n = 0; n < 2; ++n) _Pragma("unroll") for (int k = 0; k < 2; ++k) dst[n][k] = *(const PG8_LAS bf16x8*)(lds + PG8_SB(b, h) + boff + n * 2048 + k * 1024); } while (0)
; #define PG8_MMA(ai, bj, At, Bt) do { __builtin_amdgcn_s_setprio(1); _Pragma("unroll") for (int m = 0; m < 4; ++m) _Pragma("unroll") for (int n = 0; n < 2; ++n) _Pragma("unroll") for (int k = 0; k < 2; ++k) \
;         acc[ai][bj][m][n] = __builtin_amdgcn_mfma_f32_16x16x32_bf16(Bt[n][k], At[m][k], acc[ai][bj][m][n], 0, 0, 0); __builtin_amdgcn_s_setprio(0); } while (0)
; #define PG8_WAIT_V(n) asm volatile("s_waitcnt vmcnt(" #n ")" ::: "memory")
; #define PG8_WAIT_L(n) asm volatile("s_waitcnt lgkmcnt(" #n ")" ::: "memory")
; #define PG8_BAR __builtin_amdgcn_s_barrier()
; #define PG8_SCHED __builtin_amdgcn_sched_barrier(0)
; template <class Epi, class Sched, bool ALIGN_EPI = false, bool SP2 = false>
; __device__ __forceinline__ void gemm_phase(PG8_LAS unsigned char* lds, const Gemm g, const Sched& S, const Epi& E, const int tid_) {
;     ...
;             PG8_WAIT_V(8); PG8_WAIT_L(0); PG8_BAR; PG8_MMA(1, 0, At, B0); PG8_MMA(1, 1, At, B1); PG8_BAR; PG8_SCHED;
;             PG8_LDB(B0, 1, 0); PG8_LDB(B1, 1, 1); PG8_SCHED; PG8_LDA(At, 1, 0); PG8_STAGE(PG8_SA(0, 1), a2 + hstep, voffA);
;             PG8_WAIT_V(8); PG8_WAIT_L(0); PG8_BAR; PG8_MMA(0, 0, At, B0); PG8_MMA(0, 1, At, B1); PG8_BAR; PG8_SCHED;
.Lpeel2_mx1:
	s_waitcnt lgkmcnt(0)
	s_barrier
	s_waitcnt lgkmcnt(0)
	v_mfma_f32_16x16x32_bf16 v[80:83], v[12:15], v[164:167], 0
	v_mfma_f32_16x16x32_bf16 v[76:79], v[36:39], v[164:167], 0
	v_mfma_f32_16x16x32_bf16 v[64:67], v[12:15], v[198:201], 0
	v_mfma_f32_16x16x32_bf16 v[60:63], v[36:39], v[198:201], 0
	v_mfma_f32_16x16x32_bf16 v[48:51], v[12:15], v[206:209], 0
	v_mfma_f32_16x16x32_bf16 v[44:47], v[36:39], v[206:209], 0
	v_mfma_f32_16x16x32_bf16 v[12:15], v[12:15], v[214:217], 0
	v_mfma_f32_16x16x32_bf16 v[80:83], v[16:19], v[168:171], v[80:83]
	v_mfma_f32_16x16x32_bf16 v[76:79], v[40:43], v[168:171], v[76:79]
	v_mfma_f32_16x16x32_bf16 v[64:67], v[16:19], v[202:205], v[64:67]
	v_mfma_f32_16x16x32_bf16 v[60:63], v[40:43], v[202:205], v[60:63]
	v_mfma_f32_16x16x32_bf16 v[48:51], v[16:19], v[210:213], v[48:51]
	v_mfma_f32_16x16x32_bf16 v[44:47], v[40:43], v[210:213], v[44:47]
	v_mfma_f32_16x16x32_bf16 v[12:15], v[16:19], v[218:221], v[12:15]
	v_mfma_f32_16x16x32_bf16 v[16:19], v[36:39], v[214:217], 0
	v_mfma_f32_16x16x32_bf16 v[16:19], v[40:43], v[218:221], v[16:19]
	v_mfma_f32_16x16x32_bf16 v[20:23], v[148:151], v[164:167], 0
	v_mfma_f32_16x16x32_bf16 v[36:39], v[152:155], v[168:171], v[20:23]
	v_mfma_f32_16x16x32_bf16 v[20:23], v[156:159], v[164:167], 0
	v_mfma_f32_16x16x32_bf16 v[40:43], v[160:163], v[168:171], v[20:23]
	v_mfma_f32_16x16x32_bf16 v[20:23], v[148:151], v[198:201], 0
	v_mfma_f32_16x16x32_bf16 v[56:59], v[152:155], v[202:205], v[20:23]
	v_mfma_f32_16x16x32_bf16 v[20:23], v[156:159], v[198:201], 0
	v_mfma_f32_16x16x32_bf16 v[52:55], v[160:163], v[202:205], v[20:23]
	v_mfma_f32_16x16x32_bf16 v[20:23], v[148:151], v[206:209], 0
	v_mfma_f32_16x16x32_bf16 v[32:35], v[152:155], v[210:213], v[20:23]
	v_mfma_f32_16x16x32_bf16 v[20:23], v[156:159], v[206:209], 0
	v_mfma_f32_16x16x32_bf16 v[8:11], v[148:151], v[214:217], 0
	v_mfma_f32_16x16x32_bf16 v[4:7], v[156:159], v[214:217], 0
	v_mfma_f32_16x16x32_bf16 v[28:31], v[160:163], v[210:213], v[20:23]
	v_mfma_f32_16x16x32_bf16 v[8:11], v[152:155], v[218:221], v[8:11]
	v_mfma_f32_16x16x32_bf16 v[4:7], v[160:163], v[218:221], v[4:7]
	s_barrier
	v_add_u32_e32 v72, s71, v197
	v_add_u32_e32 v160, s76, v197
	ds_read_b128 v[20:23], v72
	ds_read_b128 v[24:27], v72 offset:1024
	ds_read_b128 v[68:71], v72 offset:2048
	ds_read_b128 v[72:75], v72 offset:3072
	ds_read_b128 v[148:151], v160
	ds_read_b128 v[152:155], v160 offset:1024
	ds_read_b128 v[156:159], v160 offset:2048
	ds_read_b128 v[160:163], v160 offset:3072
	s_add_u32 s10, s10, s34
	s_addc_u32 s11, s11, s35
	s_mov_b32 m0, s69
	v_lshl_add_u64 v[232:233], s[10:11], 0, v[0:1]
	ds_read_b128 v[164:167], v238 offset:32768
	ds_read_b128 v[168:171], v238 offset:33792
	ds_read_b128 v[198:201], v238 offset:34816
	ds_read_b128 v[202:205], v238 offset:35840
	ds_read_b128 v[206:209], v238 offset:36864
	ds_read_b128 v[210:213], v238 offset:37888
	ds_read_b128 v[214:217], v238 offset:38912
	ds_read_b128 v[218:221], v238 offset:39936
	global_load_lds_dwordx4 v[232:233], off
	s_mov_b32 m0, s70
	v_lshl_add_u64 v[232:233], s[10:11], 0, v[174:175]
	global_load_lds_dwordx4 v[232:233], off
	s_waitcnt vmcnt(8)
	s_waitcnt lgkmcnt(0)
	s_barrier
	s_waitcnt lgkmcnt(0)
	v_mfma_f32_16x16x32_bf16 v[144:147], v[20:23], v[164:167], v[144:147]
	v_mfma_f32_16x16x32_bf16 v[140:143], v[68:71], v[164:167], v[140:143]
	v_mfma_f32_16x16x32_bf16 v[128:131], v[20:23], v[198:201], v[128:131]
	v_mfma_f32_16x16x32_bf16 v[124:127], v[68:71], v[198:201], v[124:127]
	v_mfma_f32_16x16x32_bf16 v[112:115], v[20:23], v[206:209], v[112:115]
	v_mfma_f32_16x16x32_bf16 v[108:111], v[68:71], v[206:209], v[108:111]
	v_mfma_f32_16x16x32_bf16 v[96:99], v[20:23], v[214:217], v[96:99]
	v_mfma_f32_16x16x32_bf16 v[92:95], v[68:71], v[214:217], v[92:95]
	v_mfma_f32_16x16x32_bf16 v[144:147], v[24:27], v[168:171], v[144:147]
	v_mfma_f32_16x16x32_bf16 v[140:143], v[72:75], v[168:171], v[140:143]
	v_mfma_f32_16x16x32_bf16 v[128:131], v[24:27], v[202:205], v[128:131]
	v_mfma_f32_16x16x32_bf16 v[124:127], v[72:75], v[202:205], v[124:127]
	v_mfma_f32_16x16x32_bf16 v[112:115], v[24:27], v[210:213], v[112:115]
	v_mfma_f32_16x16x32_bf16 v[108:111], v[72:75], v[210:213], v[108:111]
	v_mfma_f32_16x16x32_bf16 v[96:99], v[24:27], v[218:221], v[96:99]
	v_mfma_f32_16x16x32_bf16 v[92:95], v[72:75], v[218:221], v[92:95]
	v_mfma_f32_16x16x32_bf16 v[136:139], v[148:151], v[164:167], v[136:139]
	v_mfma_f32_16x16x32_bf16 v[132:135], v[156:159], v[164:167], v[132:135]
	v_mfma_f32_16x16x32_bf16 v[120:123], v[148:151], v[198:201], v[120:123]
	v_mfma_f32_16x16x32_bf16 v[116:119], v[156:159], v[198:201], v[116:119]
	v_mfma_f32_16x16x32_bf16 v[104:107], v[148:151], v[206:209], v[104:107]
	v_mfma_f32_16x16x32_bf16 v[100:103], v[156:159], v[206:209], v[100:103]
	v_mfma_f32_16x16x32_bf16 v[88:91], v[148:151], v[214:217], v[88:91]
	v_mfma_f32_16x16x32_bf16 v[84:87], v[156:159], v[214:217], v[84:87]
	v_mfma_f32_16x16x32_bf16 v[136:139], v[152:155], v[168:171], v[136:139]
	v_mfma_f32_16x16x32_bf16 v[132:135], v[160:163], v[168:171], v[132:135]
	v_mfma_f32_16x16x32_bf16 v[120:123], v[152:155], v[202:205], v[120:123]
	v_mfma_f32_16x16x32_bf16 v[116:119], v[160:163], v[202:205], v[116:119]
	v_mfma_f32_16x16x32_bf16 v[104:107], v[152:155], v[210:213], v[104:107]
	v_mfma_f32_16x16x32_bf16 v[100:103], v[160:163], v[210:213], v[100:103]
	v_mfma_f32_16x16x32_bf16 v[88:91], v[152:155], v[218:221], v[88:91]
	v_mfma_f32_16x16x32_bf16 v[84:87], v[160:163], v[218:221], v[84:87]
	s_barrier
; #define PG8_STAGE(bufoff, gbase, voff) do { _Pragma("unroll") for (int _i = 0; _i < 2; ++_i) \
;         __builtin_amdgcn_global_load_lds((const unsigned*)((const char*)(gbase) + (voff)[_i]), (PG8_LAS unsigned*)(lds + (bufoff) + ldsw + _i * 8192), 16, 0, 0); } while (0)
; #define PG8_LDA(dst, b, h) do { _Pragma("unroll") for (int m = 0; m < 4; ++m) _Pragma("unroll") for (int k = 0; k < 2; ++k) dst[m][k] = *(const PG8_LAS bf16x8*)(lds + PG8_SA(b, h) + aoff + m * 2048 + k * 1024); } while (0)
; #define PG8_LDB(dst, b, h) do { _Pragma("unroll") for (int n = 0; n < 2; ++n) _Pragma("unroll") for (int k = 0; k < 2; ++k) dst[n][k] = *(const PG8_LAS bf16x8*)(lds + PG8_SB(b, h) + boff + n * 2048 + k * 1024); } while (0)
; #define PG8_MMA(ai, bj, At, Bt) do { __builtin_amdgcn_s_setprio(1); _Pragma("unroll") for (int m = 0; m < 4; ++m) _Pragma("unroll") for (int n = 0; n < 2; ++n) _Pragma("unroll") for (int k = 0; k < 2; ++k) \
;         acc[ai][bj][m][n] = __builtin_amdgcn_mfma_f32_16x16x32_bf16(Bt[n][k], At[m][k], acc[ai][bj][m][n], 0, 0, 0); __builtin_amdgcn_s_setprio(0); } while (0)
; #define PG8_WAIT_V(n) asm volatile("s_waitcnt vmcnt(" #n ")" ::: "memory")
; #define PG8_WAIT_L(n) asm volatile("s_waitcnt lgkmcnt(" #n ")" ::: "memory")
; #define PG8_BAR __builtin_amdgcn_s_barrier()
; #define PG8_SCHED __builtin_amdgcn_sched_barrier(0)
; template <class Epi, class Sched, bool ALIGN_EPI = false, bool SP2 = false>
; __device__ __forceinline__ void gemm_phase(PG8_LAS unsigned char* lds, const Gemm g, const Sched& S, const Epi& E, const int tid_) {
;     ...
;             PG8_LDB(B0, 0, 0); PG8_LDB(B1, 0, 1); PG8_SCHED; PG8_LDA(At, 0, 0); PG8_STAGE(PG8_SA(1, 1), a1 + hstep, voffA);
;             PG8_WAIT_V(8); PG8_WAIT_L(0); PG8_BAR; PG8_MMA(0, 0, At, B0); PG8_MMA(0, 1, At, B1); PG8_BAR; PG8_SCHED;
;     ...
;             PG8_LDA(At, 1, 1); PG8_STAGE(PG8_SB(1, 0), b3, voffB); PG8_STAGE(PG8_SB(1, 1), b3 + hstepB, voffB); PG8_STAGE(PG8_SA(1, 0), a3, voffA);
;             PG8_WAIT_V(8); PG8_WAIT_L(0); PG8_BAR; PG8_MMA(1, 0, At, B0); PG8_MMA(1, 1, At, B1); PG8_BAR; PG8_SCHED;
	s_mov_b32 m0, s72
	v_lshl_add_u64 v[194:195], v[194:195], 0, s[96:97]
	ds_read_b128 v[164:167], v238 offset:49152
	ds_read_b128 v[168:171], v238 offset:50176
	ds_read_b128 v[198:201], v238 offset:51200
	ds_read_b128 v[202:205], v238 offset:52224
	ds_read_b128 v[206:209], v238 offset:53248
	ds_read_b128 v[210:213], v238 offset:54272
	ds_read_b128 v[214:217], v238 offset:55296
	ds_read_b128 v[218:221], v238 offset:56320
	global_load_lds_dwordx4 v[194:195], off
	s_mov_b32 m0, s73
	v_lshl_add_u64 v[194:195], v[222:223], 0, s[96:97]
	global_load_lds_dwordx4 v[194:195], off
	s_mov_b32 m0, s77
	v_lshl_add_u64 v[194:195], v[224:225], 0, s[96:97]
	global_load_lds_dwordx4 v[194:195], off
	s_mov_b32 m0, s80
	v_lshl_add_u64 v[194:195], v[226:227], 0, s[96:97]
	global_load_lds_dwordx4 v[194:195], off
	s_mov_b32 m0, s74
	v_lshl_add_u64 v[194:195], v[228:229], 0, s[96:97]
	global_load_lds_dwordx4 v[194:195], off
	s_mov_b32 m0, s75
	v_lshl_add_u64 v[194:195], v[230:231], 0, s[96:97]
	global_load_lds_dwordx4 v[194:195], off
	s_waitcnt vmcnt(8)
	s_waitcnt lgkmcnt(0)
	s_barrier
	s_waitcnt lgkmcnt(0)
	v_mfma_f32_16x16x32_bf16 v[80:83], v[20:23], v[164:167], v[80:83]
	v_mfma_f32_16x16x32_bf16 v[64:67], v[20:23], v[198:201], v[64:67]
	v_mfma_f32_16x16x32_bf16 v[48:51], v[20:23], v[206:209], v[48:51]
	v_mfma_f32_16x16x32_bf16 v[12:15], v[20:23], v[214:217], v[12:15]
	v_mfma_f32_16x16x32_bf16 v[80:83], v[24:27], v[168:171], v[80:83]
	v_mfma_f32_16x16x32_bf16 v[76:79], v[68:71], v[164:167], v[76:79]
	v_mfma_f32_16x16x32_bf16 v[64:67], v[24:27], v[202:205], v[64:67]
	v_mfma_f32_16x16x32_bf16 v[60:63], v[68:71], v[198:201], v[60:63]
	v_mfma_f32_16x16x32_bf16 v[48:51], v[24:27], v[210:213], v[48:51]
	v_mfma_f32_16x16x32_bf16 v[44:47], v[68:71], v[206:209], v[44:47]
	v_mfma_f32_16x16x32_bf16 v[24:27], v[24:27], v[218:221], v[12:15]
	v_mfma_f32_16x16x32_bf16 v[12:15], v[68:71], v[214:217], v[16:19]
	v_mfma_f32_16x16x32_bf16 v[76:79], v[72:75], v[168:171], v[76:79]
	v_mfma_f32_16x16x32_bf16 v[60:63], v[72:75], v[202:205], v[60:63]
	v_mfma_f32_16x16x32_bf16 v[44:47], v[72:75], v[210:213], v[44:47]
	v_mfma_f32_16x16x32_bf16 v[20:23], v[72:75], v[218:221], v[12:15]
	v_mfma_f32_16x16x32_bf16 v[12:15], v[148:151], v[164:167], v[36:39]
	v_mfma_f32_16x16x32_bf16 v[72:75], v[152:155], v[168:171], v[12:15]
	v_mfma_f32_16x16x32_bf16 v[12:15], v[156:159], v[164:167], v[40:43]
	v_mfma_f32_16x16x32_bf16 v[68:71], v[160:163], v[168:171], v[12:15]
	v_mfma_f32_16x16x32_bf16 v[12:15], v[148:151], v[198:201], v[56:59]
	v_mfma_f32_16x16x32_bf16 v[56:59], v[152:155], v[202:205], v[12:15]
	v_mfma_f32_16x16x32_bf16 v[12:15], v[156:159], v[198:201], v[52:55]
	v_mfma_f32_16x16x32_bf16 v[52:55], v[160:163], v[202:205], v[12:15]
	v_mfma_f32_16x16x32_bf16 v[12:15], v[148:151], v[206:209], v[32:35]
	v_mfma_f32_16x16x32_bf16 v[32:35], v[152:155], v[210:213], v[12:15]
	v_mfma_f32_16x16x32_bf16 v[12:15], v[156:159], v[206:209], v[28:31]
	v_mfma_f32_16x16x32_bf16 v[8:11], v[148:151], v[214:217], v[8:11]
	v_mfma_f32_16x16x32_bf16 v[4:7], v[156:159], v[214:217], v[4:7]
	v_mfma_f32_16x16x32_bf16 v[28:31], v[160:163], v[210:213], v[12:15]
	v_mfma_f32_16x16x32_bf16 v[8:11], v[152:155], v[218:221], v[8:11]
	v_mfma_f32_16x16x32_bf16 v[4:7], v[160:163], v[218:221], v[4:7]
	s_barrier
	s_add_u32 s8, s8, 0x100
	s_addc_u32 s9, s9, 0
	s_add_u32 s2, s2, 0x100
	s_addc_u32 s3, s3, 0
	s_cmp_ge_u32 s12, s81
	s_mov_b32 s10, s12
.LBB0_369:
	v_add_u32_e32 v40, s61, v197
	v_add_u32_e32 v160, s64, v197
	ds_read_b128 v[12:15], v40
	ds_read_b128 v[16:19], v40 offset:1024
	ds_read_b128 v[36:39], v40 offset:2048
	ds_read_b128 v[40:43], v40 offset:3072
	ds_read_b128 v[148:151], v160
	ds_read_b128 v[152:155], v160 offset:1024
	ds_read_b128 v[156:159], v160 offset:2048
	ds_read_b128 v[160:163], v160 offset:3072
	s_add_i32 s12, s10, 2
	s_add_u32 s13, s8, 0x80
	s_addc_u32 s11, s9, 0
	s_cmp_eq_u32 s82, s10
	s_cselect_b32 s10, s48, s13
	s_cselect_b32 s11, s49, s11
	s_cselect_b32 s53, s51, s3
	s_cselect_b32 s52, s50, s2
	v_lshl_add_u64 v[194:195], s[8:9], 0, v[190:191]
	s_add_i32 m0, s67, 0xc000
	ds_read_b128 v[164:167], v238
	ds_read_b128 v[168:171], v238 offset:1024
	ds_read_b128 v[198:201], v238 offset:2048
	ds_read_b128 v[202:205], v238 offset:3072
	ds_read_b128 v[206:209], v238 offset:4096
	ds_read_b128 v[210:213], v238 offset:5120
	ds_read_b128 v[214:217], v238 offset:6144
	ds_read_b128 v[218:221], v238 offset:7168
	global_load_lds_dwordx4 v[194:195], off
	v_lshl_add_u64 v[194:195], s[8:9], 0, v[192:193]
	s_add_i32 m0, s67, 0xe000
	s_nop 0
	global_load_lds_dwordx4 v[194:195], off
	s_waitcnt vmcnt(8)
	s_waitcnt lgkmcnt(0)
	s_barrier
; #define PG8_STAGE(bufoff, gbase, voff) do { _Pragma("unroll") for (int _i = 0; _i < 2; ++_i) \
;         __builtin_amdgcn_global_load_lds((const unsigned*)((const char*)(gbase) + (voff)[_i]), (PG8_LAS unsigned*)(lds + (bufoff) + ldsw + _i * 8192), 16, 0, 0); } while (0)
; #define PG8_LDA(dst, b, h) do { _Pragma("unroll") for (int m = 0; m < 4; ++m) _Pragma("unroll") for (int k = 0; k < 2; ++k) dst[m][k] = *(const PG8_LAS bf16x8*)(lds + PG8_SA(b, h) + aoff + m * 2048 + k * 1024); } while (0)
; #define PG8_LDB(dst, b, h) do { _Pragma("unroll") for (int n = 0; n < 2; ++n) _Pragma("unroll") for (int k = 0; k < 2; ++k) dst[n][k] = *(const PG8_LAS bf16x8*)(lds + PG8_SB(b, h) + boff + n * 2048 + k * 1024); } while (0)
; #define PG8_MMA(ai, bj, At, Bt) do { __builtin_amdgcn_s_setprio(1); _Pragma("unroll") for (int m = 0; m < 4; ++m) _Pragma("unroll") for (int n = 0; n < 2; ++n) _Pragma("unroll") for (int k = 0; k < 2; ++k) \
;         acc[ai][bj][m][n] = __builtin_amdgcn_mfma_f32_16x16x32_bf16(Bt[n][k], At[m][k], acc[ai][bj][m][n], 0, 0, 0); __builtin_amdgcn_s_setprio(0); } while (0)
; #define PG8_WAIT_V(n) asm volatile("s_waitcnt vmcnt(" #n ")" ::: "memory")
; #define PG8_WAIT_L(n) asm volatile("s_waitcnt lgkmcnt(" #n ")" ::: "memory")
; #define PG8_BAR __builtin_amdgcn_s_barrier()
; #define PG8_SCHED __builtin_amdgcn_sched_barrier(0)
; template <class Epi, class Sched, bool ALIGN_EPI = false, bool SP2 = false>
; __device__ __forceinline__ void gemm_phase(PG8_LAS unsigned char* lds, const Gemm g, const Sched& S, const Epi& E, const int tid_) {
;     ...
;             PG8_WAIT_V(8); PG8_WAIT_L(0); PG8_BAR; PG8_MMA(0, 0, At, B0); PG8_MMA(0, 1, At, B1); PG8_BAR; PG8_SCHED;
;             PG8_LDA(At, 0, 1); PG8_STAGE(PG8_SB(0, 0), b2, voffB); PG8_STAGE(PG8_SB(0, 1), b2 + hstepB, voffB); PG8_STAGE(PG8_SA(0, 0), a2, voffA);
;             PG8_WAIT_V(8); PG8_WAIT_L(0); PG8_BAR; PG8_MMA(1, 0, At, B0); PG8_MMA(1, 1, At, B1); PG8_BAR; PG8_SCHED;
;             PG8_LDB(B0, 1, 0); PG8_LDB(B1, 1, 1); PG8_SCHED; PG8_LDA(At, 1, 0); PG8_STAGE(PG8_SA(0, 1), a2 + hstep, voffA);
;             PG8_WAIT_V(8); PG8_WAIT_L(0); PG8_BAR; PG8_MMA(0, 0, At, B0); PG8_MMA(0, 1, At, B1); PG8_BAR; PG8_SCHED;
	s_waitcnt lgkmcnt(0)
	v_mfma_f32_16x16x32_bf16 v[144:147], v[12:15], v[164:167], v[144:147]
	v_mfma_f32_16x16x32_bf16 v[140:143], v[36:39], v[164:167], v[140:143]
	v_mfma_f32_16x16x32_bf16 v[128:131], v[12:15], v[198:201], v[128:131]
	v_mfma_f32_16x16x32_bf16 v[124:127], v[36:39], v[198:201], v[124:127]
	v_mfma_f32_16x16x32_bf16 v[112:115], v[12:15], v[206:209], v[112:115]
	v_mfma_f32_16x16x32_bf16 v[108:111], v[36:39], v[206:209], v[108:111]
	v_mfma_f32_16x16x32_bf16 v[96:99], v[12:15], v[214:217], v[96:99]
	v_mfma_f32_16x16x32_bf16 v[92:95], v[36:39], v[214:217], v[92:95]
	v_mfma_f32_16x16x32_bf16 v[144:147], v[16:19], v[168:171], v[144:147]
	v_mfma_f32_16x16x32_bf16 v[140:143], v[40:43], v[168:171], v[140:143]
	v_mfma_f32_16x16x32_bf16 v[128:131], v[16:19], v[202:205], v[128:131]
	v_mfma_f32_16x16x32_bf16 v[124:127], v[40:43], v[202:205], v[124:127]
	v_mfma_f32_16x16x32_bf16 v[112:115], v[16:19], v[210:213], v[112:115]
	v_mfma_f32_16x16x32_bf16 v[108:111], v[40:43], v[210:213], v[108:111]
	v_mfma_f32_16x16x32_bf16 v[96:99], v[16:19], v[218:221], v[96:99]
	v_mfma_f32_16x16x32_bf16 v[92:95], v[40:43], v[218:221], v[92:95]
	v_mfma_f32_16x16x32_bf16 v[136:139], v[148:151], v[164:167], v[136:139]
	v_mfma_f32_16x16x32_bf16 v[132:135], v[156:159], v[164:167], v[132:135]
	v_mfma_f32_16x16x32_bf16 v[120:123], v[148:151], v[198:201], v[120:123]
	v_mfma_f32_16x16x32_bf16 v[116:119], v[156:159], v[198:201], v[116:119]
	v_mfma_f32_16x16x32_bf16 v[104:107], v[148:151], v[206:209], v[104:107]
	v_mfma_f32_16x16x32_bf16 v[100:103], v[156:159], v[206:209], v[100:103]
	v_mfma_f32_16x16x32_bf16 v[88:91], v[148:151], v[214:217], v[88:91]
	v_mfma_f32_16x16x32_bf16 v[84:87], v[156:159], v[214:217], v[84:87]
	v_mfma_f32_16x16x32_bf16 v[136:139], v[152:155], v[168:171], v[136:139]
	v_mfma_f32_16x16x32_bf16 v[132:135], v[160:163], v[168:171], v[132:135]
	v_mfma_f32_16x16x32_bf16 v[120:123], v[152:155], v[202:205], v[120:123]
	v_mfma_f32_16x16x32_bf16 v[116:119], v[160:163], v[202:205], v[116:119]
	v_mfma_f32_16x16x32_bf16 v[104:107], v[152:155], v[210:213], v[104:107]
	v_mfma_f32_16x16x32_bf16 v[100:103], v[160:163], v[210:213], v[100:103]
	v_mfma_f32_16x16x32_bf16 v[88:91], v[152:155], v[218:221], v[88:91]
	v_mfma_f32_16x16x32_bf16 v[84:87], v[160:163], v[218:221], v[84:87]
	s_barrier
	s_mov_b32 m0, s62
	v_lshl_add_u64 v[194:195], s[52:53], 0, v[172:173]
	v_lshl_add_u64 v[222:223], s[52:53], 0, v[176:177]
	s_add_u32 s52, s52, s38
	ds_read_b128 v[164:167], v238 offset:16384
	ds_read_b128 v[168:171], v238 offset:17408
	ds_read_b128 v[198:201], v238 offset:18432
	ds_read_b128 v[202:205], v238 offset:19456
	ds_read_b128 v[206:209], v238 offset:20480
	ds_read_b128 v[210:213], v238 offset:21504
	ds_read_b128 v[214:217], v238 offset:22528
	ds_read_b128 v[218:221], v238 offset:23552
	global_load_lds_dwordx4 v[194:195], off
	s_mov_b32 m0, s63
	s_addc_u32 s53, s53, s39
	global_load_lds_dwordx4 v[222:223], off
	v_lshl_add_u64 v[224:225], s[52:53], 0, v[172:173]
	s_mov_b32 m0, s65
	v_lshl_add_u64 v[226:227], s[52:53], 0, v[176:177]
	global_load_lds_dwordx4 v[224:225], off
	s_mov_b32 m0, s66
	v_lshl_add_u64 v[228:229], s[10:11], 0, v[0:1]
	global_load_lds_dwordx4 v[226:227], off
	s_mov_b32 m0, s67
	v_lshl_add_u64 v[230:231], s[10:11], 0, v[174:175]
	global_load_lds_dwordx4 v[228:229], off
	s_mov_b32 m0, s68
	s_nop 0
	global_load_lds_dwordx4 v[230:231], off
	s_waitcnt vmcnt(8)
	s_waitcnt lgkmcnt(0)
	s_barrier
	s_waitcnt lgkmcnt(0)
	v_mfma_f32_16x16x32_bf16 v[80:83], v[12:15], v[164:167], v[80:83]
	v_mfma_f32_16x16x32_bf16 v[76:79], v[36:39], v[164:167], v[76:79]
	v_mfma_f32_16x16x32_bf16 v[64:67], v[12:15], v[198:201], v[64:67]
	v_mfma_f32_16x16x32_bf16 v[60:63], v[36:39], v[198:201], v[60:63]
	v_mfma_f32_16x16x32_bf16 v[48:51], v[12:15], v[206:209], v[48:51]
	v_mfma_f32_16x16x32_bf16 v[44:47], v[36:39], v[206:209], v[44:47]
	v_mfma_f32_16x16x32_bf16 v[12:15], v[12:15], v[214:217], v[24:27]
	v_mfma_f32_16x16x32_bf16 v[80:83], v[16:19], v[168:171], v[80:83]
	v_mfma_f32_16x16x32_bf16 v[76:79], v[40:43], v[168:171], v[76:79]
	v_mfma_f32_16x16x32_bf16 v[64:67], v[16:19], v[202:205], v[64:67]
	v_mfma_f32_16x16x32_bf16 v[60:63], v[40:43], v[202:205], v[60:63]
	v_mfma_f32_16x16x32_bf16 v[48:51], v[16:19], v[210:213], v[48:51]
	v_mfma_f32_16x16x32_bf16 v[44:47], v[40:43], v[210:213], v[44:47]
	v_mfma_f32_16x16x32_bf16 v[12:15], v[16:19], v[218:221], v[12:15]
	v_mfma_f32_16x16x32_bf16 v[16:19], v[36:39], v[214:217], v[20:23]
	v_mfma_f32_16x16x32_bf16 v[16:19], v[40:43], v[218:221], v[16:19]
	v_mfma_f32_16x16x32_bf16 v[20:23], v[148:151], v[164:167], v[72:75]
	v_mfma_f32_16x16x32_bf16 v[36:39], v[152:155], v[168:171], v[20:23]
	v_mfma_f32_16x16x32_bf16 v[20:23], v[156:159], v[164:167], v[68:71]
	v_mfma_f32_16x16x32_bf16 v[40:43], v[160:163], v[168:171], v[20:23]
	v_mfma_f32_16x16x32_bf16 v[20:23], v[148:151], v[198:201], v[56:59]
	v_mfma_f32_16x16x32_bf16 v[56:59], v[152:155], v[202:205], v[20:23]
	v_mfma_f32_16x16x32_bf16 v[20:23], v[156:159], v[198:201], v[52:55]
	v_mfma_f32_16x16x32_bf16 v[52:55], v[160:163], v[202:205], v[20:23]
	v_mfma_f32_16x16x32_bf16 v[20:23], v[148:151], v[206:209], v[32:35]
	v_mfma_f32_16x16x32_bf16 v[32:35], v[152:155], v[210:213], v[20:23]
	v_mfma_f32_16x16x32_bf16 v[20:23], v[156:159], v[206:209], v[28:31]
	v_mfma_f32_16x16x32_bf16 v[8:11], v[148:151], v[214:217], v[8:11]
	v_mfma_f32_16x16x32_bf16 v[4:7], v[156:159], v[214:217], v[4:7]
	v_mfma_f32_16x16x32_bf16 v[28:31], v[160:163], v[210:213], v[20:23]
	v_mfma_f32_16x16x32_bf16 v[8:11], v[152:155], v[218:221], v[8:11]
	v_mfma_f32_16x16x32_bf16 v[4:7], v[160:163], v[218:221], v[4:7]
	s_barrier
; #define PG8_STAGE(bufoff, gbase, voff) do { _Pragma("unroll") for (int _i = 0; _i < 2; ++_i) \
;         __builtin_amdgcn_global_load_lds((const unsigned*)((const char*)(gbase) + (voff)[_i]), (PG8_LAS unsigned*)(lds + (bufoff) + ldsw + _i * 8192), 16, 0, 0); } while (0)
; #define PG8_LDA(dst, b, h) do { _Pragma("unroll") for (int m = 0; m < 4; ++m) _Pragma("unroll") for (int k = 0; k < 2; ++k) dst[m][k] = *(const PG8_LAS bf16x8*)(lds + PG8_SA(b, h) + aoff + m * 2048 + k * 1024); } while (0)
; #define PG8_LDB(dst, b, h) do { _Pragma("unroll") for (int n = 0; n < 2; ++n) _Pragma("unroll") for (int k = 0; k < 2; ++k) dst[n][k] = *(const PG8_LAS bf16x8*)(lds + PG8_SB(b, h) + boff + n * 2048 + k * 1024); } while (0)
; #define PG8_MMA(ai, bj, At, Bt) do { __builtin_amdgcn_s_setprio(1); _Pragma("unroll") for (int m = 0; m < 4; ++m) _Pragma("unroll") for (int n = 0; n < 2; ++n) _Pragma("unroll") for (int k = 0; k < 2; ++k) \
;         acc[ai][bj][m][n] = __builtin_amdgcn_mfma_f32_16x16x32_bf16(Bt[n][k], At[m][k], acc[ai][bj][m][n], 0, 0, 0); __builtin_amdgcn_s_setprio(0); } while (0)
; #define PG8_WAIT_V(n) asm volatile("s_waitcnt vmcnt(" #n ")" ::: "memory")
; #define PG8_WAIT_L(n) asm volatile("s_waitcnt lgkmcnt(" #n ")" ::: "memory")
; #define PG8_BAR __builtin_amdgcn_s_barrier()
; #define PG8_SCHED __builtin_amdgcn_sched_barrier(0)
; template <class Epi, class Sched, bool ALIGN_EPI = false, bool SP2 = false>
; __device__ __forceinline__ void gemm_phase(PG8_LAS unsigned char* lds, const Gemm g, const Sched& S, const Epi& E, const int tid_) {
;     ...
;             PG8_LDB(B0, 1, 0); PG8_LDB(B1, 1, 1); PG8_SCHED; PG8_LDA(At, 1, 0); PG8_STAGE(PG8_SA(0, 1), a2 + hstep, voffA);
;             PG8_WAIT_V(8); PG8_WAIT_L(0); PG8_BAR; PG8_MMA(0, 0, At, B0); PG8_MMA(0, 1, At, B1); PG8_BAR; PG8_SCHED;
;             PG8_LDA(At, 1, 1); PG8_STAGE(PG8_SB(1, 0), b3, voffB); PG8_STAGE(PG8_SB(1, 1), b3 + hstepB, voffB); PG8_STAGE(PG8_SA(1, 0), a3, voffA);
;             PG8_WAIT_V(8); PG8_WAIT_L(0); PG8_BAR; PG8_MMA(1, 0, At, B0); PG8_MMA(1, 1, At, B1); PG8_BAR; PG8_SCHED;
	v_add_u32_e32 v72, s71, v197
	v_add_u32_e32 v160, s76, v197
	ds_read_b128 v[20:23], v72
	ds_read_b128 v[24:27], v72 offset:1024
	ds_read_b128 v[68:71], v72 offset:2048
	ds_read_b128 v[72:75], v72 offset:3072
	ds_read_b128 v[148:151], v160
	ds_read_b128 v[152:155], v160 offset:1024
	ds_read_b128 v[156:159], v160 offset:2048
	ds_read_b128 v[160:163], v160 offset:3072
	s_add_u32 s10, s10, s34
	s_addc_u32 s11, s11, s35
	s_mov_b32 m0, s69
	v_lshl_add_u64 v[232:233], s[10:11], 0, v[0:1]
	ds_read_b128 v[164:167], v238 offset:32768
	ds_read_b128 v[168:171], v238 offset:33792
	ds_read_b128 v[198:201], v238 offset:34816
	ds_read_b128 v[202:205], v238 offset:35840
	ds_read_b128 v[206:209], v238 offset:36864
	ds_read_b128 v[210:213], v238 offset:37888
	ds_read_b128 v[214:217], v238 offset:38912
	ds_read_b128 v[218:221], v238 offset:39936
	global_load_lds_dwordx4 v[232:233], off
	s_mov_b32 m0, s70
	v_lshl_add_u64 v[232:233], s[10:11], 0, v[174:175]
	global_load_lds_dwordx4 v[232:233], off
	s_waitcnt vmcnt(8)
	s_waitcnt lgkmcnt(0)
	s_barrier
	s_waitcnt lgkmcnt(0)
	v_mfma_f32_16x16x32_bf16 v[144:147], v[20:23], v[164:167], v[144:147]
	v_mfma_f32_16x16x32_bf16 v[140:143], v[68:71], v[164:167], v[140:143]
	v_mfma_f32_16x16x32_bf16 v[128:131], v[20:23], v[198:201], v[128:131]
	v_mfma_f32_16x16x32_bf16 v[124:127], v[68:71], v[198:201], v[124:127]
	v_mfma_f32_16x16x32_bf16 v[112:115], v[20:23], v[206:209], v[112:115]
	v_mfma_f32_16x16x32_bf16 v[108:111], v[68:71], v[206:209], v[108:111]
	v_mfma_f32_16x16x32_bf16 v[96:99], v[20:23], v[214:217], v[96:99]
	v_mfma_f32_16x16x32_bf16 v[92:95], v[68:71], v[214:217], v[92:95]
	v_mfma_f32_16x16x32_bf16 v[144:147], v[24:27], v[168:171], v[144:147]
	v_mfma_f32_16x16x32_bf16 v[140:143], v[72:75], v[168:171], v[140:143]
	v_mfma_f32_16x16x32_bf16 v[128:131], v[24:27], v[202:205], v[128:131]
	v_mfma_f32_16x16x32_bf16 v[124:127], v[72:75], v[202:205], v[124:127]
	v_mfma_f32_16x16x32_bf16 v[112:115], v[24:27], v[210:213], v[112:115]
	v_mfma_f32_16x16x32_bf16 v[108:111], v[72:75], v[210:213], v[108:111]
	v_mfma_f32_16x16x32_bf16 v[96:99], v[24:27], v[218:221], v[96:99]
	v_mfma_f32_16x16x32_bf16 v[92:95], v[72:75], v[218:221], v[92:95]
	v_mfma_f32_16x16x32_bf16 v[136:139], v[148:151], v[164:167], v[136:139]
	v_mfma_f32_16x16x32_bf16 v[132:135], v[156:159], v[164:167], v[132:135]
	v_mfma_f32_16x16x32_bf16 v[120:123], v[148:151], v[198:201], v[120:123]
	v_mfma_f32_16x16x32_bf16 v[116:119], v[156:159], v[198:201], v[116:119]
	v_mfma_f32_16x16x32_bf16 v[104:107], v[148:151], v[206:209], v[104:107]
	v_mfma_f32_16x16x32_bf16 v[100:103], v[156:159], v[206:209], v[100:103]
	v_mfma_f32_16x16x32_bf16 v[88:91], v[148:151], v[214:217], v[88:91]
	v_mfma_f32_16x16x32_bf16 v[84:87], v[156:159], v[214:217], v[84:87]
	v_mfma_f32_16x16x32_bf16 v[136:139], v[152:155], v[168:171], v[136:139]
	v_mfma_f32_16x16x32_bf16 v[132:135], v[160:163], v[168:171], v[132:135]
	v_mfma_f32_16x16x32_bf16 v[120:123], v[152:155], v[202:205], v[120:123]
	v_mfma_f32_16x16x32_bf16 v[116:119], v[160:163], v[202:205], v[116:119]
	v_mfma_f32_16x16x32_bf16 v[104:107], v[152:155], v[210:213], v[104:107]
	v_mfma_f32_16x16x32_bf16 v[100:103], v[160:163], v[210:213], v[100:103]
	v_mfma_f32_16x16x32_bf16 v[88:91], v[152:155], v[218:221], v[88:91]
	v_mfma_f32_16x16x32_bf16 v[84:87], v[160:163], v[218:221], v[84:87]
	s_barrier
	s_mov_b32 m0, s72
	v_lshl_add_u64 v[194:195], v[194:195], 0, s[96:97]
	ds_read_b128 v[164:167], v238 offset:49152
	ds_read_b128 v[168:171], v238 offset:50176
	ds_read_b128 v[198:201], v238 offset:51200
	ds_read_b128 v[202:205], v238 offset:52224
	ds_read_b128 v[206:209], v238 offset:53248
	ds_read_b128 v[210:213], v238 offset:54272
	ds_read_b128 v[214:217], v238 offset:55296
	ds_read_b128 v[218:221], v238 offset:56320
	global_load_lds_dwordx4 v[194:195], off
	s_mov_b32 m0, s73
	v_lshl_add_u64 v[194:195], v[222:223], 0, s[96:97]
	global_load_lds_dwordx4 v[194:195], off
	s_mov_b32 m0, s77
	v_lshl_add_u64 v[194:195], v[224:225], 0, s[96:97]
	global_load_lds_dwordx4 v[194:195], off
	s_mov_b32 m0, s80
	v_lshl_add_u64 v[194:195], v[226:227], 0, s[96:97]
	global_load_lds_dwordx4 v[194:195], off
	s_mov_b32 m0, s74
	v_lshl_add_u64 v[194:195], v[228:229], 0, s[96:97]
	global_load_lds_dwordx4 v[194:195], off
	s_mov_b32 m0, s75
	v_lshl_add_u64 v[194:195], v[230:231], 0, s[96:97]
	global_load_lds_dwordx4 v[194:195], off
	s_waitcnt vmcnt(8)
	s_waitcnt lgkmcnt(0)
	s_barrier
	s_waitcnt lgkmcnt(0)
	v_mfma_f32_16x16x32_bf16 v[80:83], v[20:23], v[164:167], v[80:83]
	v_mfma_f32_16x16x32_bf16 v[64:67], v[20:23], v[198:201], v[64:67]
	v_mfma_f32_16x16x32_bf16 v[48:51], v[20:23], v[206:209], v[48:51]
	v_mfma_f32_16x16x32_bf16 v[12:15], v[20:23], v[214:217], v[12:15]
	v_mfma_f32_16x16x32_bf16 v[80:83], v[24:27], v[168:171], v[80:83]
	v_mfma_f32_16x16x32_bf16 v[76:79], v[68:71], v[164:167], v[76:79]
	v_mfma_f32_16x16x32_bf16 v[64:67], v[24:27], v[202:205], v[64:67]
	v_mfma_f32_16x16x32_bf16 v[60:63], v[68:71], v[198:201], v[60:63]
	v_mfma_f32_16x16x32_bf16 v[48:51], v[24:27], v[210:213], v[48:51]
	v_mfma_f32_16x16x32_bf16 v[44:47], v[68:71], v[206:209], v[44:47]
	v_mfma_f32_16x16x32_bf16 v[24:27], v[24:27], v[218:221], v[12:15]
	v_mfma_f32_16x16x32_bf16 v[12:15], v[68:71], v[214:217], v[16:19]
	v_mfma_f32_16x16x32_bf16 v[76:79], v[72:75], v[168:171], v[76:79]
	v_mfma_f32_16x16x32_bf16 v[60:63], v[72:75], v[202:205], v[60:63]
	v_mfma_f32_16x16x32_bf16 v[44:47], v[72:75], v[210:213], v[44:47]
	v_mfma_f32_16x16x32_bf16 v[20:23], v[72:75], v[218:221], v[12:15]
	v_mfma_f32_16x16x32_bf16 v[12:15], v[148:151], v[164:167], v[36:39]
	v_mfma_f32_16x16x32_bf16 v[72:75], v[152:155], v[168:171], v[12:15]
	v_mfma_f32_16x16x32_bf16 v[12:15], v[156:159], v[164:167], v[40:43]
	v_mfma_f32_16x16x32_bf16 v[68:71], v[160:163], v[168:171], v[12:15]
	v_mfma_f32_16x16x32_bf16 v[12:15], v[148:151], v[198:201], v[56:59]
	v_mfma_f32_16x16x32_bf16 v[56:59], v[152:155], v[202:205], v[12:15]
	v_mfma_f32_16x16x32_bf16 v[12:15], v[156:159], v[198:201], v[52:55]
	v_mfma_f32_16x16x32_bf16 v[52:55], v[160:163], v[202:205], v[12:15]
	v_mfma_f32_16x16x32_bf16 v[12:15], v[148:151], v[206:209], v[32:35]
	v_mfma_f32_16x16x32_bf16 v[32:35], v[152:155], v[210:213], v[12:15]
	v_mfma_f32_16x16x32_bf16 v[12:15], v[156:159], v[206:209], v[28:31]
	v_mfma_f32_16x16x32_bf16 v[8:11], v[148:151], v[214:217], v[8:11]
	v_mfma_f32_16x16x32_bf16 v[4:7], v[156:159], v[214:217], v[4:7]
	v_mfma_f32_16x16x32_bf16 v[28:31], v[160:163], v[210:213], v[12:15]
	v_mfma_f32_16x16x32_bf16 v[8:11], v[152:155], v[218:221], v[8:11]
	v_mfma_f32_16x16x32_bf16 v[4:7], v[160:163], v[218:221], v[4:7]
	s_barrier
	s_add_u32 s8, s8, 0x100
	s_addc_u32 s9, s9, 0
	s_add_u32 s2, s2, 0x100
	s_addc_u32 s3, s3, 0
	s_cmp_ge_u32 s12, s81
	s_mov_b32 s10, s12
	s_cbranch_scc0 .LBB0_369
	s_and_b64 vcc, exec, s[84:85]
	s_cbranch_vccz .LBB0_372
	s_barrier

; #define PG8_STAGE(bufoff, gbase, voff) do { _Pragma("unroll") for (int _i = 0; _i < 2; ++_i) \
;         __builtin_amdgcn_global_load_lds((const unsigned*)((const char*)(gbase) + (voff)[_i]), (PG8_LAS unsigned*)(lds + (bufoff) + ldsw + _i * 8192), 16, 0, 0); } while (0)
; #define PG8_LDA(dst, b, h) do { _Pragma("unroll") for (int m = 0; m < 4; ++m) _Pragma("unroll") for (int k = 0; k < 2; ++k) dst[m][k] = *(const PG8_LAS bf16x8*)(lds + PG8_SA(b, h) + aoff + m * 2048 + k * 1024); } while (0)
; #define PG8_LDB(dst, b, h) do { _Pragma("unroll") for (int n = 0; n < 2; ++n) _Pragma("unroll") for (int k = 0; k < 2; ++k) dst[n][k] = *(const PG8_LAS bf16x8*)(lds + PG8_SB(b, h) + boff + n * 2048 + k * 1024); } while (0)
; #define PG8_MMA(ai, bj, At, Bt) do { __builtin_amdgcn_s_setprio(1); _Pragma("unroll") for (int m = 0; m < 4; ++m) _Pragma("unroll") for (int n = 0; n < 2; ++n) _Pragma("unroll") for (int k = 0; k < 2; ++k) \
;         acc[ai][bj][m][n] = __builtin_amdgcn_mfma_f32_16x16x32_bf16(Bt[n][k], At[m][k], acc[ai][bj][m][n], 0, 0, 0); __builtin_amdgcn_s_setprio(0); } while (0)
; #define PG8_WAIT_V(n) asm volatile("s_waitcnt vmcnt(" #n ")" ::: "memory")
; #define PG8_WAIT_L(n) asm volatile("s_waitcnt lgkmcnt(" #n ")" ::: "memory")
; #define PG8_BAR __builtin_amdgcn_s_barrier()
; #define PG8_SCHED __builtin_amdgcn_sched_barrier(0)
; template <class Epi, class Sched, bool ALIGN_EPI = false, bool SP2 = false>
; __device__ __forceinline__ void gemm_phase(PG8_LAS unsigned char* lds, const Gemm g, const Sched& S, const Epi& E, const int tid_) {
;     ...
;             PG8_WAIT_V(8); PG8_WAIT_L(0); PG8_BAR; PG8_MMA(1, 0, At, B0); PG8_MMA(1, 1, At, B1); PG8_BAR; PG8_SCHED;
;             PG8_LDB(B0, 1, 0); PG8_LDB(B1, 1, 1); PG8_SCHED; PG8_LDA(At, 1, 0); PG8_STAGE(PG8_SA(0, 1), a2 + hstep, voffA);
;             PG8_WAIT_V(8); PG8_WAIT_L(0); PG8_BAR; PG8_MMA(0, 0, At, B0); PG8_MMA(0, 1, At, B1); PG8_BAR; PG8_SCHED;
.Lpeel2_rs1:
	s_waitcnt lgkmcnt(0)
	s_barrier
	s_waitcnt lgkmcnt(0)
	v_mfma_f32_16x16x32_bf16 v[80:83], v[36:39], v[164:167], 0
	v_mfma_f32_16x16x32_bf16 v[76:79], v[48:51], v[164:167], 0
	v_mfma_f32_16x16x32_bf16 v[64:67], v[36:39], v[172:175], 0
	v_mfma_f32_16x16x32_bf16 v[60:63], v[48:51], v[172:175], 0
	v_mfma_f32_16x16x32_bf16 v[32:35], v[36:39], v[196:199], 0
	v_mfma_f32_16x16x32_bf16 v[28:31], v[48:51], v[196:199], 0
	v_mfma_f32_16x16x32_bf16 v[16:19], v[36:39], v[204:207], 0
	v_mfma_f32_16x16x32_bf16 v[12:15], v[48:51], v[204:207], 0
	v_mfma_f32_16x16x32_bf16 v[80:83], v[40:43], v[168:171], v[80:83]
	v_mfma_f32_16x16x32_bf16 v[76:79], v[56:59], v[168:171], v[76:79]
	v_mfma_f32_16x16x32_bf16 v[64:67], v[40:43], v[176:179], v[64:67]
	v_mfma_f32_16x16x32_bf16 v[60:63], v[56:59], v[176:179], v[60:63]
	v_mfma_f32_16x16x32_bf16 v[32:35], v[40:43], v[200:203], v[32:35]
	v_mfma_f32_16x16x32_bf16 v[28:31], v[56:59], v[200:203], v[28:31]
	v_mfma_f32_16x16x32_bf16 v[16:19], v[40:43], v[208:211], v[16:19]
	v_mfma_f32_16x16x32_bf16 v[12:15], v[56:59], v[208:211], v[12:15]
	v_mfma_f32_16x16x32_bf16 v[44:47], v[156:159], v[172:175], 0
	v_mfma_f32_16x16x32_bf16 v[24:27], v[148:151], v[196:199], 0
	v_mfma_f32_16x16x32_bf16 v[20:23], v[156:159], v[196:199], 0
	v_mfma_f32_16x16x32_bf16 v[8:11], v[148:151], v[204:207], 0
	v_mfma_f32_16x16x32_bf16 v[4:7], v[156:159], v[204:207], 0
	v_mfma_f32_16x16x32_bf16 v[36:39], v[148:151], v[164:167], 0
	v_mfma_f32_16x16x32_bf16 v[40:43], v[156:159], v[164:167], 0
	v_mfma_f32_16x16x32_bf16 v[48:51], v[148:151], v[172:175], 0
	v_mfma_f32_16x16x32_bf16 v[44:47], v[160:163], v[176:179], v[44:47]
	v_mfma_f32_16x16x32_bf16 v[24:27], v[152:155], v[200:203], v[24:27]
	v_mfma_f32_16x16x32_bf16 v[20:23], v[160:163], v[200:203], v[20:23]
	v_mfma_f32_16x16x32_bf16 v[8:11], v[152:155], v[208:211], v[8:11]
	v_mfma_f32_16x16x32_bf16 v[4:7], v[160:163], v[208:211], v[4:7]
	v_mfma_f32_16x16x32_bf16 v[36:39], v[152:155], v[168:171], v[36:39]
	v_mfma_f32_16x16x32_bf16 v[40:43], v[160:163], v[168:171], v[40:43]
	v_mfma_f32_16x16x32_bf16 v[48:51], v[152:155], v[176:179], v[48:51]
	s_barrier
	v_add_u32_e32 v72, s63, v214
	v_add_u32_e32 v160, s68, v214
	ds_read_b128 v[52:55], v72
	ds_read_b128 v[56:59], v72 offset:1024
	ds_read_b128 v[68:71], v72 offset:2048
	ds_read_b128 v[72:75], v72 offset:3072
	ds_read_b128 v[148:151], v160
	ds_read_b128 v[152:155], v160 offset:1024
	ds_read_b128 v[156:159], v160 offset:2048
	ds_read_b128 v[160:163], v160 offset:3072
	s_add_u32 s14, s14, s24
	s_addc_u32 s15, s15, 0
	s_mov_b32 m0, s61
	v_lshl_add_u64 v[228:229], s[14:15], 0, v[0:1]
	ds_read_b128 v[164:167], v216 offset:32768
	ds_read_b128 v[168:171], v216 offset:33792
	ds_read_b128 v[172:175], v216 offset:34816
	ds_read_b128 v[176:179], v216 offset:35840
	ds_read_b128 v[196:199], v216 offset:36864
	ds_read_b128 v[200:203], v216 offset:37888
	ds_read_b128 v[204:207], v216 offset:38912
	ds_read_b128 v[208:211], v216 offset:39936
	global_load_lds_dwordx4 v[228:229], off
	s_mov_b32 m0, s62
	v_lshl_add_u64 v[228:229], s[14:15], 0, v[188:189]
	global_load_lds_dwordx4 v[228:229], off
	s_waitcnt vmcnt(8)
	s_waitcnt lgkmcnt(0)
	s_barrier
	s_waitcnt lgkmcnt(0)
	v_mfma_f32_16x16x32_bf16 v[144:147], v[52:55], v[164:167], v[144:147]
	v_mfma_f32_16x16x32_bf16 v[140:143], v[68:71], v[164:167], v[140:143]
	v_mfma_f32_16x16x32_bf16 v[128:131], v[52:55], v[172:175], v[128:131]
	v_mfma_f32_16x16x32_bf16 v[124:127], v[68:71], v[172:175], v[124:127]
	v_mfma_f32_16x16x32_bf16 v[112:115], v[52:55], v[196:199], v[112:115]
	v_mfma_f32_16x16x32_bf16 v[108:111], v[68:71], v[196:199], v[108:111]
	v_mfma_f32_16x16x32_bf16 v[96:99], v[52:55], v[204:207], v[96:99]
	v_mfma_f32_16x16x32_bf16 v[92:95], v[68:71], v[204:207], v[92:95]
	v_mfma_f32_16x16x32_bf16 v[144:147], v[56:59], v[168:171], v[144:147]
	v_mfma_f32_16x16x32_bf16 v[140:143], v[72:75], v[168:171], v[140:143]
	v_mfma_f32_16x16x32_bf16 v[128:131], v[56:59], v[176:179], v[128:131]
	v_mfma_f32_16x16x32_bf16 v[124:127], v[72:75], v[176:179], v[124:127]
	v_mfma_f32_16x16x32_bf16 v[112:115], v[56:59], v[200:203], v[112:115]
	v_mfma_f32_16x16x32_bf16 v[108:111], v[72:75], v[200:203], v[108:111]
	v_mfma_f32_16x16x32_bf16 v[96:99], v[56:59], v[208:211], v[96:99]
	v_mfma_f32_16x16x32_bf16 v[92:95], v[72:75], v[208:211], v[92:95]
	v_mfma_f32_16x16x32_bf16 v[136:139], v[148:151], v[164:167], v[136:139]
	v_mfma_f32_16x16x32_bf16 v[132:135], v[156:159], v[164:167], v[132:135]
	v_mfma_f32_16x16x32_bf16 v[120:123], v[148:151], v[172:175], v[120:123]
	v_mfma_f32_16x16x32_bf16 v[116:119], v[156:159], v[172:175], v[116:119]
	v_mfma_f32_16x16x32_bf16 v[104:107], v[148:151], v[196:199], v[104:107]
	v_mfma_f32_16x16x32_bf16 v[100:103], v[156:159], v[196:199], v[100:103]
	v_mfma_f32_16x16x32_bf16 v[88:91], v[148:151], v[204:207], v[88:91]
	v_mfma_f32_16x16x32_bf16 v[84:87], v[156:159], v[204:207], v[84:87]
	v_mfma_f32_16x16x32_bf16 v[136:139], v[152:155], v[168:171], v[136:139]
	v_mfma_f32_16x16x32_bf16 v[132:135], v[160:163], v[168:171], v[132:135]
	v_mfma_f32_16x16x32_bf16 v[120:123], v[152:155], v[176:179], v[120:123]
	v_mfma_f32_16x16x32_bf16 v[116:119], v[160:163], v[176:179], v[116:119]
	v_mfma_f32_16x16x32_bf16 v[104:107], v[152:155], v[200:203], v[104:107]
	v_mfma_f32_16x16x32_bf16 v[100:103], v[160:163], v[200:203], v[100:103]
	v_mfma_f32_16x16x32_bf16 v[88:91], v[152:155], v[208:211], v[88:91]
	v_mfma_f32_16x16x32_bf16 v[84:87], v[160:163], v[208:211], v[84:87]
	s_barrier
; #define PG8_STAGE(bufoff, gbase, voff) do { _Pragma("unroll") for (int _i = 0; _i < 2; ++_i) \
;         __builtin_amdgcn_global_load_lds((const unsigned*)((const char*)(gbase) + (voff)[_i]), (PG8_LAS unsigned*)(lds + (bufoff) + ldsw + _i * 8192), 16, 0, 0); } while (0)
; #define PG8_LDA(dst, b, h) do { _Pragma("unroll") for (int m = 0; m < 4; ++m) _Pragma("unroll") for (int k = 0; k < 2; ++k) dst[m][k] = *(const PG8_LAS bf16x8*)(lds + PG8_SA(b, h) + aoff + m * 2048 + k * 1024); } while (0)
; #define PG8_LDB(dst, b, h) do { _Pragma("unroll") for (int n = 0; n < 2; ++n) _Pragma("unroll") for (int k = 0; k < 2; ++k) dst[n][k] = *(const PG8_LAS bf16x8*)(lds + PG8_SB(b, h) + boff + n * 2048 + k * 1024); } while (0)
; #define PG8_MMA(ai, bj, At, Bt) do { __builtin_amdgcn_s_setprio(1); _Pragma("unroll") for (int m = 0; m < 4; ++m) _Pragma("unroll") for (int n = 0; n < 2; ++n) _Pragma("unroll") for (int k = 0; k < 2; ++k) \
;         acc[ai][bj][m][n] = __builtin_amdgcn_mfma_f32_16x16x32_bf16(Bt[n][k], At[m][k], acc[ai][bj][m][n], 0, 0, 0); __builtin_amdgcn_s_setprio(0); } while (0)
; #define PG8_WAIT_V(n) asm volatile("s_waitcnt vmcnt(" #n ")" ::: "memory")
; #define PG8_WAIT_L(n) asm volatile("s_waitcnt lgkmcnt(" #n ")" ::: "memory")
; #define PG8_BAR __builtin_amdgcn_s_barrier()
; #define PG8_SCHED __builtin_amdgcn_sched_barrier(0)
; template <class Epi, class Sched, bool ALIGN_EPI = false, bool SP2 = false>
; __device__ __forceinline__ void gemm_phase(PG8_LAS unsigned char* lds, const Gemm g, const Sched& S, const Epi& E, const int tid_) {
;     ...
;             PG8_LDB(B0, 0, 0); PG8_LDB(B1, 0, 1); PG8_SCHED; PG8_LDA(At, 0, 0); PG8_STAGE(PG8_SA(1, 1), a1 + hstep, voffA);
;             PG8_WAIT_V(8); PG8_WAIT_L(0); PG8_BAR; PG8_MMA(0, 0, At, B0); PG8_MMA(0, 1, At, B1); PG8_BAR; PG8_SCHED;
;     ...
;             PG8_LDA(At, 1, 1); PG8_STAGE(PG8_SB(1, 0), b3, voffB); PG8_STAGE(PG8_SB(1, 1), b3 + hstepB, voffB); PG8_STAGE(PG8_SA(1, 0), a3, voffA);
;             PG8_WAIT_V(8); PG8_WAIT_L(0); PG8_BAR; PG8_MMA(1, 0, At, B0); PG8_MMA(1, 1, At, B1); PG8_BAR; PG8_SCHED;
	s_mov_b32 m0, s64
	v_lshl_add_u64 v[212:213], v[212:213], 0, s[96:97]
	ds_read_b128 v[164:167], v216 offset:49152
	ds_read_b128 v[168:171], v216 offset:50176
	ds_read_b128 v[172:175], v216 offset:51200
	ds_read_b128 v[176:179], v216 offset:52224
	ds_read_b128 v[196:199], v216 offset:53248
	ds_read_b128 v[200:203], v216 offset:54272
	ds_read_b128 v[204:207], v216 offset:55296
	ds_read_b128 v[208:211], v216 offset:56320
	global_load_lds_dwordx4 v[212:213], off
	s_mov_b32 m0, s65
	v_lshl_add_u64 v[212:213], v[218:219], 0, s[96:97]
	global_load_lds_dwordx4 v[212:213], off
	s_mov_b32 m0, s69
	v_lshl_add_u64 v[212:213], v[220:221], 0, s[96:97]
	global_load_lds_dwordx4 v[212:213], off
	s_mov_b32 m0, s70
	v_lshl_add_u64 v[212:213], v[222:223], 0, s[96:97]
	global_load_lds_dwordx4 v[212:213], off
	s_mov_b32 m0, s66
	v_lshl_add_u64 v[212:213], v[224:225], 0, s[96:97]
	global_load_lds_dwordx4 v[212:213], off
	s_mov_b32 m0, s67
	v_lshl_add_u64 v[212:213], v[226:227], 0, s[96:97]
	global_load_lds_dwordx4 v[212:213], off
	s_waitcnt vmcnt(8)
	s_waitcnt lgkmcnt(0)
	s_barrier
	s_waitcnt lgkmcnt(0)
	v_mfma_f32_16x16x32_bf16 v[80:83], v[52:55], v[164:167], v[80:83]
	v_mfma_f32_16x16x32_bf16 v[76:79], v[68:71], v[164:167], v[76:79]
	v_mfma_f32_16x16x32_bf16 v[64:67], v[52:55], v[172:175], v[64:67]
	v_mfma_f32_16x16x32_bf16 v[60:63], v[68:71], v[172:175], v[60:63]
	v_mfma_f32_16x16x32_bf16 v[32:35], v[52:55], v[196:199], v[32:35]
	v_mfma_f32_16x16x32_bf16 v[28:31], v[68:71], v[196:199], v[28:31]
	v_mfma_f32_16x16x32_bf16 v[16:19], v[52:55], v[204:207], v[16:19]
	v_mfma_f32_16x16x32_bf16 v[12:15], v[68:71], v[204:207], v[12:15]
	v_mfma_f32_16x16x32_bf16 v[80:83], v[56:59], v[168:171], v[80:83]
	v_mfma_f32_16x16x32_bf16 v[76:79], v[72:75], v[168:171], v[76:79]
	v_mfma_f32_16x16x32_bf16 v[64:67], v[56:59], v[176:179], v[64:67]
	v_mfma_f32_16x16x32_bf16 v[60:63], v[72:75], v[176:179], v[60:63]
	v_mfma_f32_16x16x32_bf16 v[32:35], v[56:59], v[200:203], v[32:35]
	v_mfma_f32_16x16x32_bf16 v[28:31], v[72:75], v[200:203], v[28:31]
	v_mfma_f32_16x16x32_bf16 v[16:19], v[56:59], v[208:211], v[16:19]
	v_mfma_f32_16x16x32_bf16 v[12:15], v[72:75], v[208:211], v[12:15]
	v_mfma_f32_16x16x32_bf16 v[36:39], v[148:151], v[164:167], v[36:39]
	v_mfma_f32_16x16x32_bf16 v[72:75], v[152:155], v[168:171], v[36:39]
	v_mfma_f32_16x16x32_bf16 v[36:39], v[156:159], v[164:167], v[40:43]
	v_mfma_f32_16x16x32_bf16 v[68:71], v[160:163], v[168:171], v[36:39]
	v_mfma_f32_16x16x32_bf16 v[36:39], v[148:151], v[172:175], v[48:51]
	v_mfma_f32_16x16x32_bf16 v[52:55], v[152:155], v[176:179], v[36:39]
	v_mfma_f32_16x16x32_bf16 v[36:39], v[156:159], v[172:175], v[44:47]
	v_mfma_f32_16x16x32_bf16 v[24:27], v[148:151], v[196:199], v[24:27]
	v_mfma_f32_16x16x32_bf16 v[20:23], v[156:159], v[196:199], v[20:23]
	v_mfma_f32_16x16x32_bf16 v[8:11], v[148:151], v[204:207], v[8:11]
	v_mfma_f32_16x16x32_bf16 v[4:7], v[156:159], v[204:207], v[4:7]
	v_mfma_f32_16x16x32_bf16 v[44:47], v[160:163], v[176:179], v[36:39]
	v_mfma_f32_16x16x32_bf16 v[24:27], v[152:155], v[200:203], v[24:27]
	v_mfma_f32_16x16x32_bf16 v[20:23], v[160:163], v[200:203], v[20:23]
	v_mfma_f32_16x16x32_bf16 v[8:11], v[152:155], v[208:211], v[8:11]
	v_mfma_f32_16x16x32_bf16 v[4:7], v[160:163], v[208:211], v[4:7]
	s_barrier
	s_add_u32 s12, s12, 0x100
	s_addc_u32 s13, s13, 0
	s_add_u32 s2, s2, 0x100
	s_addc_u32 s3, s3, 0
	s_cmp_ge_u32 s46, s73
	s_mov_b32 s14, s46
.LBB0_528:
	v_add_u32_e32 v56, s53, v214
	v_add_u32_e32 v160, s56, v214
	ds_read_b128 v[36:39], v56
	ds_read_b128 v[40:43], v56 offset:1024
	ds_read_b128 v[48:51], v56 offset:2048
	ds_read_b128 v[56:59], v56 offset:3072
	ds_read_b128 v[148:151], v160
	ds_read_b128 v[152:155], v160 offset:1024
	ds_read_b128 v[156:159], v160 offset:2048
	ds_read_b128 v[160:163], v160 offset:3072
	s_add_i32 s46, s14, 2
	s_add_u32 s47, s12, 0x80
	s_addc_u32 s15, s13, 0
	s_cmp_eq_u32 s74, s14
	s_cselect_b32 s14, s42, s47
	s_cselect_b32 s15, s43, s15
	s_cselect_b32 s49, s45, s3
	s_cselect_b32 s48, s44, s2
	v_lshl_add_u64 v[212:213], s[12:13], 0, v[192:193]
	s_add_i32 m0, s59, 0xc000
	ds_read_b128 v[164:167], v216
	ds_read_b128 v[168:171], v216 offset:1024
	ds_read_b128 v[172:175], v216 offset:2048
	ds_read_b128 v[176:179], v216 offset:3072
	ds_read_b128 v[196:199], v216 offset:4096
	ds_read_b128 v[200:203], v216 offset:5120
	ds_read_b128 v[204:207], v216 offset:6144
	ds_read_b128 v[208:211], v216 offset:7168
	global_load_lds_dwordx4 v[212:213], off
	v_lshl_add_u64 v[212:213], s[12:13], 0, v[194:195]
	s_add_i32 m0, s59, 0xe000
	s_nop 0
	global_load_lds_dwordx4 v[212:213], off
	s_waitcnt vmcnt(8)
	s_waitcnt lgkmcnt(0)
	s_barrier
; #define PG8_STAGE(bufoff, gbase, voff) do { _Pragma("unroll") for (int _i = 0; _i < 2; ++_i) \
;         __builtin_amdgcn_global_load_lds((const unsigned*)((const char*)(gbase) + (voff)[_i]), (PG8_LAS unsigned*)(lds + (bufoff) + ldsw + _i * 8192), 16, 0, 0); } while (0)
; #define PG8_LDA(dst, b, h) do { _Pragma("unroll") for (int m = 0; m < 4; ++m) _Pragma("unroll") for (int k = 0; k < 2; ++k) dst[m][k] = *(const PG8_LAS bf16x8*)(lds + PG8_SA(b, h) + aoff + m * 2048 + k * 1024); } while (0)
; #define PG8_LDB(dst, b, h) do { _Pragma("unroll") for (int n = 0; n < 2; ++n) _Pragma("unroll") for (int k = 0; k < 2; ++k) dst[n][k] = *(const PG8_LAS bf16x8*)(lds + PG8_SB(b, h) + boff + n * 2048 + k * 1024); } while (0)
; #define PG8_MMA(ai, bj, At, Bt) do { __builtin_amdgcn_s_setprio(1); _Pragma("unroll") for (int m = 0; m < 4; ++m) _Pragma("unroll") for (int n = 0; n < 2; ++n) _Pragma("unroll") for (int k = 0; k < 2; ++k) \
;         acc[ai][bj][m][n] = __builtin_amdgcn_mfma_f32_16x16x32_bf16(Bt[n][k], At[m][k], acc[ai][bj][m][n], 0, 0, 0); __builtin_amdgcn_s_setprio(0); } while (0)
; #define PG8_WAIT_V(n) asm volatile("s_waitcnt vmcnt(" #n ")" ::: "memory")
; #define PG8_WAIT_L(n) asm volatile("s_waitcnt lgkmcnt(" #n ")" ::: "memory")
; #define PG8_BAR __builtin_amdgcn_s_barrier()
; #define PG8_SCHED __builtin_amdgcn_sched_barrier(0)
; template <class Epi, class Sched, bool ALIGN_EPI = false, bool SP2 = false>
; __device__ __forceinline__ void gemm_phase(PG8_LAS unsigned char* lds, const Gemm g, const Sched& S, const Epi& E, const int tid_) {
;     ...
;             PG8_WAIT_V(8); PG8_WAIT_L(0); PG8_BAR; PG8_MMA(0, 0, At, B0); PG8_MMA(0, 1, At, B1); PG8_BAR; PG8_SCHED;
;             PG8_LDA(At, 0, 1); PG8_STAGE(PG8_SB(0, 0), b2, voffB); PG8_STAGE(PG8_SB(0, 1), b2 + hstepB, voffB); PG8_STAGE(PG8_SA(0, 0), a2, voffA);
;             PG8_WAIT_V(8); PG8_WAIT_L(0); PG8_BAR; PG8_MMA(1, 0, At, B0); PG8_MMA(1, 1, At, B1); PG8_BAR; PG8_SCHED;
;             PG8_LDB(B0, 1, 0); PG8_LDB(B1, 1, 1); PG8_SCHED; PG8_LDA(At, 1, 0); PG8_STAGE(PG8_SA(0, 1), a2 + hstep, voffA);
;             PG8_WAIT_V(8); PG8_WAIT_L(0); PG8_BAR; PG8_MMA(0, 0, At, B0); PG8_MMA(0, 1, At, B1); PG8_BAR; PG8_SCHED;
	s_waitcnt lgkmcnt(0)
	v_mfma_f32_16x16x32_bf16 v[144:147], v[36:39], v[164:167], v[144:147]
	v_mfma_f32_16x16x32_bf16 v[140:143], v[48:51], v[164:167], v[140:143]
	v_mfma_f32_16x16x32_bf16 v[128:131], v[36:39], v[172:175], v[128:131]
	v_mfma_f32_16x16x32_bf16 v[124:127], v[48:51], v[172:175], v[124:127]
	v_mfma_f32_16x16x32_bf16 v[112:115], v[36:39], v[196:199], v[112:115]
	v_mfma_f32_16x16x32_bf16 v[108:111], v[48:51], v[196:199], v[108:111]
	v_mfma_f32_16x16x32_bf16 v[96:99], v[36:39], v[204:207], v[96:99]
	v_mfma_f32_16x16x32_bf16 v[92:95], v[48:51], v[204:207], v[92:95]
	v_mfma_f32_16x16x32_bf16 v[144:147], v[40:43], v[168:171], v[144:147]
	v_mfma_f32_16x16x32_bf16 v[140:143], v[56:59], v[168:171], v[140:143]
	v_mfma_f32_16x16x32_bf16 v[128:131], v[40:43], v[176:179], v[128:131]
	v_mfma_f32_16x16x32_bf16 v[124:127], v[56:59], v[176:179], v[124:127]
	v_mfma_f32_16x16x32_bf16 v[112:115], v[40:43], v[200:203], v[112:115]
	v_mfma_f32_16x16x32_bf16 v[108:111], v[56:59], v[200:203], v[108:111]
	v_mfma_f32_16x16x32_bf16 v[96:99], v[40:43], v[208:211], v[96:99]
	v_mfma_f32_16x16x32_bf16 v[92:95], v[56:59], v[208:211], v[92:95]
	v_mfma_f32_16x16x32_bf16 v[136:139], v[148:151], v[164:167], v[136:139]
	v_mfma_f32_16x16x32_bf16 v[132:135], v[156:159], v[164:167], v[132:135]
	v_mfma_f32_16x16x32_bf16 v[120:123], v[148:151], v[172:175], v[120:123]
	v_mfma_f32_16x16x32_bf16 v[116:119], v[156:159], v[172:175], v[116:119]
	v_mfma_f32_16x16x32_bf16 v[104:107], v[148:151], v[196:199], v[104:107]
	v_mfma_f32_16x16x32_bf16 v[100:103], v[156:159], v[196:199], v[100:103]
	v_mfma_f32_16x16x32_bf16 v[88:91], v[148:151], v[204:207], v[88:91]
	v_mfma_f32_16x16x32_bf16 v[84:87], v[156:159], v[204:207], v[84:87]
	v_mfma_f32_16x16x32_bf16 v[136:139], v[152:155], v[168:171], v[136:139]
	v_mfma_f32_16x16x32_bf16 v[132:135], v[160:163], v[168:171], v[132:135]
	v_mfma_f32_16x16x32_bf16 v[120:123], v[152:155], v[176:179], v[120:123]
	v_mfma_f32_16x16x32_bf16 v[116:119], v[160:163], v[176:179], v[116:119]
	v_mfma_f32_16x16x32_bf16 v[104:107], v[152:155], v[200:203], v[104:107]
	v_mfma_f32_16x16x32_bf16 v[100:103], v[160:163], v[200:203], v[100:103]
	v_mfma_f32_16x16x32_bf16 v[88:91], v[152:155], v[208:211], v[88:91]
	v_mfma_f32_16x16x32_bf16 v[84:87], v[160:163], v[208:211], v[84:87]
	s_barrier
	s_mov_b32 m0, s54
	v_lshl_add_u64 v[212:213], s[48:49], 0, v[2:3]
	v_lshl_add_u64 v[218:219], s[48:49], 0, v[190:191]
	s_add_u32 s48, s48, s52
	ds_read_b128 v[164:167], v216 offset:16384
	ds_read_b128 v[168:171], v216 offset:17408
	ds_read_b128 v[172:175], v216 offset:18432
	ds_read_b128 v[176:179], v216 offset:19456
	ds_read_b128 v[196:199], v216 offset:20480
	ds_read_b128 v[200:203], v216 offset:21504
	ds_read_b128 v[204:207], v216 offset:22528
	ds_read_b128 v[208:211], v216 offset:23552
	global_load_lds_dwordx4 v[212:213], off
	s_mov_b32 m0, s55
	s_addc_u32 s49, s49, 0
	global_load_lds_dwordx4 v[218:219], off
	v_lshl_add_u64 v[220:221], s[48:49], 0, v[2:3]
	s_mov_b32 m0, s57
	v_lshl_add_u64 v[222:223], s[48:49], 0, v[190:191]
	global_load_lds_dwordx4 v[220:221], off
	s_mov_b32 m0, s58
	v_lshl_add_u64 v[224:225], s[14:15], 0, v[0:1]
	global_load_lds_dwordx4 v[222:223], off
	s_mov_b32 m0, s59
	v_lshl_add_u64 v[226:227], s[14:15], 0, v[188:189]
	global_load_lds_dwordx4 v[224:225], off
	s_mov_b32 m0, s60
	s_nop 0
	global_load_lds_dwordx4 v[226:227], off
	s_waitcnt vmcnt(8)
	s_waitcnt lgkmcnt(0)
	s_barrier
	s_waitcnt lgkmcnt(0)
	v_mfma_f32_16x16x32_bf16 v[80:83], v[36:39], v[164:167], v[80:83]
	v_mfma_f32_16x16x32_bf16 v[76:79], v[48:51], v[164:167], v[76:79]
	v_mfma_f32_16x16x32_bf16 v[64:67], v[36:39], v[172:175], v[64:67]
	v_mfma_f32_16x16x32_bf16 v[60:63], v[48:51], v[172:175], v[60:63]
	v_mfma_f32_16x16x32_bf16 v[32:35], v[36:39], v[196:199], v[32:35]
	v_mfma_f32_16x16x32_bf16 v[28:31], v[48:51], v[196:199], v[28:31]
	v_mfma_f32_16x16x32_bf16 v[16:19], v[36:39], v[204:207], v[16:19]
	v_mfma_f32_16x16x32_bf16 v[12:15], v[48:51], v[204:207], v[12:15]
	v_mfma_f32_16x16x32_bf16 v[80:83], v[40:43], v[168:171], v[80:83]
	v_mfma_f32_16x16x32_bf16 v[76:79], v[56:59], v[168:171], v[76:79]
	v_mfma_f32_16x16x32_bf16 v[64:67], v[40:43], v[176:179], v[64:67]
	v_mfma_f32_16x16x32_bf16 v[60:63], v[56:59], v[176:179], v[60:63]
	v_mfma_f32_16x16x32_bf16 v[32:35], v[40:43], v[200:203], v[32:35]
	v_mfma_f32_16x16x32_bf16 v[28:31], v[56:59], v[200:203], v[28:31]
	v_mfma_f32_16x16x32_bf16 v[16:19], v[40:43], v[208:211], v[16:19]
	v_mfma_f32_16x16x32_bf16 v[12:15], v[56:59], v[208:211], v[12:15]
	v_mfma_f32_16x16x32_bf16 v[44:47], v[156:159], v[172:175], v[44:47]
	v_mfma_f32_16x16x32_bf16 v[24:27], v[148:151], v[196:199], v[24:27]
	v_mfma_f32_16x16x32_bf16 v[20:23], v[156:159], v[196:199], v[20:23]
	v_mfma_f32_16x16x32_bf16 v[8:11], v[148:151], v[204:207], v[8:11]
	v_mfma_f32_16x16x32_bf16 v[4:7], v[156:159], v[204:207], v[4:7]
	v_mfma_f32_16x16x32_bf16 v[36:39], v[148:151], v[164:167], v[72:75]
	v_mfma_f32_16x16x32_bf16 v[40:43], v[156:159], v[164:167], v[68:71]
	v_mfma_f32_16x16x32_bf16 v[48:51], v[148:151], v[172:175], v[52:55]
	v_mfma_f32_16x16x32_bf16 v[44:47], v[160:163], v[176:179], v[44:47]
	v_mfma_f32_16x16x32_bf16 v[24:27], v[152:155], v[200:203], v[24:27]
	v_mfma_f32_16x16x32_bf16 v[20:23], v[160:163], v[200:203], v[20:23]
	v_mfma_f32_16x16x32_bf16 v[8:11], v[152:155], v[208:211], v[8:11]
	v_mfma_f32_16x16x32_bf16 v[4:7], v[160:163], v[208:211], v[4:7]
	v_mfma_f32_16x16x32_bf16 v[36:39], v[152:155], v[168:171], v[36:39]
	v_mfma_f32_16x16x32_bf16 v[40:43], v[160:163], v[168:171], v[40:43]
	v_mfma_f32_16x16x32_bf16 v[48:51], v[152:155], v[176:179], v[48:51]
	s_barrier
; #define PG8_STAGE(bufoff, gbase, voff) do { _Pragma("unroll") for (int _i = 0; _i < 2; ++_i) \
;         __builtin_amdgcn_global_load_lds((const unsigned*)((const char*)(gbase) + (voff)[_i]), (PG8_LAS unsigned*)(lds + (bufoff) + ldsw + _i * 8192), 16, 0, 0); } while (0)
; #define PG8_LDA(dst, b, h) do { _Pragma("unroll") for (int m = 0; m < 4; ++m) _Pragma("unroll") for (int k = 0; k < 2; ++k) dst[m][k] = *(const PG8_LAS bf16x8*)(lds + PG8_SA(b, h) + aoff + m * 2048 + k * 1024); } while (0)
; #define PG8_LDB(dst, b, h) do { _Pragma("unroll") for (int n = 0; n < 2; ++n) _Pragma("unroll") for (int k = 0; k < 2; ++k) dst[n][k] = *(const PG8_LAS bf16x8*)(lds + PG8_SB(b, h) + boff + n * 2048 + k * 1024); } while (0)
; #define PG8_MMA(ai, bj, At, Bt) do { __builtin_amdgcn_s_setprio(1); _Pragma("unroll") for (int m = 0; m < 4; ++m) _Pragma("unroll") for (int n = 0; n < 2; ++n) _Pragma("unroll") for (int k = 0; k < 2; ++k) \
;         acc[ai][bj][m][n] = __builtin_amdgcn_mfma_f32_16x16x32_bf16(Bt[n][k], At[m][k], acc[ai][bj][m][n], 0, 0, 0); __builtin_amdgcn_s_setprio(0); } while (0)
; #define PG8_WAIT_V(n) asm volatile("s_waitcnt vmcnt(" #n ")" ::: "memory")
; #define PG8_WAIT_L(n) asm volatile("s_waitcnt lgkmcnt(" #n ")" ::: "memory")
; #define PG8_BAR __builtin_amdgcn_s_barrier()
; #define PG8_SCHED __builtin_amdgcn_sched_barrier(0)
; template <class Epi, class Sched, bool ALIGN_EPI = false, bool SP2 = false>
; __device__ __forceinline__ void gemm_phase(PG8_LAS unsigned char* lds, const Gemm g, const Sched& S, const Epi& E, const int tid_) {
;     ...
;             PG8_LDB(B0, 1, 0); PG8_LDB(B1, 1, 1); PG8_SCHED; PG8_LDA(At, 1, 0); PG8_STAGE(PG8_SA(0, 1), a2 + hstep, voffA);
;             PG8_WAIT_V(8); PG8_WAIT_L(0); PG8_BAR; PG8_MMA(0, 0, At, B0); PG8_MMA(0, 1, At, B1); PG8_BAR; PG8_SCHED;
	v_add_u32_e32 v72, s63, v214
	v_add_u32_e32 v160, s68, v214
	ds_read_b128 v[52:55], v72
	ds_read_b128 v[56:59], v72 offset:1024
	ds_read_b128 v[68:71], v72 offset:2048
	ds_read_b128 v[72:75], v72 offset:3072
	ds_read_b128 v[148:151], v160
	ds_read_b128 v[152:155], v160 offset:1024
	ds_read_b128 v[156:159], v160 offset:2048
	ds_read_b128 v[160:163], v160 offset:3072
	s_add_u32 s14, s14, s24
	s_addc_u32 s15, s15, 0
	s_mov_b32 m0, s61
	v_lshl_add_u64 v[228:229], s[14:15], 0, v[0:1]
	ds_read_b128 v[164:167], v216 offset:32768
	ds_read_b128 v[168:171], v216 offset:33792
	ds_read_b128 v[172:175], v216 offset:34816
	ds_read_b128 v[176:179], v216 offset:35840
	ds_read_b128 v[196:199], v216 offset:36864
	ds_read_b128 v[200:203], v216 offset:37888
	ds_read_b128 v[204:207], v216 offset:38912
	ds_read_b128 v[208:211], v216 offset:39936
	global_load_lds_dwordx4 v[228:229], off
	s_mov_b32 m0, s62
	v_lshl_add_u64 v[228:229], s[14:15], 0, v[188:189]
	global_load_lds_dwordx4 v[228:229], off
	s_waitcnt vmcnt(8)
	s_waitcnt lgkmcnt(0)
	s_barrier
	s_waitcnt lgkmcnt(0)
	v_mfma_f32_16x16x32_bf16 v[144:147], v[52:55], v[164:167], v[144:147]
	v_mfma_f32_16x16x32_bf16 v[140:143], v[68:71], v[164:167], v[140:143]
	v_mfma_f32_16x16x32_bf16 v[128:131], v[52:55], v[172:175], v[128:131]
	v_mfma_f32_16x16x32_bf16 v[124:127], v[68:71], v[172:175], v[124:127]
	v_mfma_f32_16x16x32_bf16 v[112:115], v[52:55], v[196:199], v[112:115]
	v_mfma_f32_16x16x32_bf16 v[108:111], v[68:71], v[196:199], v[108:111]
	v_mfma_f32_16x16x32_bf16 v[96:99], v[52:55], v[204:207], v[96:99]
	v_mfma_f32_16x16x32_bf16 v[92:95], v[68:71], v[204:207], v[92:95]
	v_mfma_f32_16x16x32_bf16 v[144:147], v[56:59], v[168:171], v[144:147]
	v_mfma_f32_16x16x32_bf16 v[140:143], v[72:75], v[168:171], v[140:143]
	v_mfma_f32_16x16x32_bf16 v[128:131], v[56:59], v[176:179], v[128:131]
	v_mfma_f32_16x16x32_bf16 v[124:127], v[72:75], v[176:179], v[124:127]
	v_mfma_f32_16x16x32_bf16 v[112:115], v[56:59], v[200:203], v[112:115]
	v_mfma_f32_16x16x32_bf16 v[108:111], v[72:75], v[200:203], v[108:111]
	v_mfma_f32_16x16x32_bf16 v[96:99], v[56:59], v[208:211], v[96:99]
	v_mfma_f32_16x16x32_bf16 v[92:95], v[72:75], v[208:211], v[92:95]
	v_mfma_f32_16x16x32_bf16 v[136:139], v[148:151], v[164:167], v[136:139]
	v_mfma_f32_16x16x32_bf16 v[132:135], v[156:159], v[164:167], v[132:135]
	v_mfma_f32_16x16x32_bf16 v[120:123], v[148:151], v[172:175], v[120:123]
	v_mfma_f32_16x16x32_bf16 v[116:119], v[156:159], v[172:175], v[116:119]
	v_mfma_f32_16x16x32_bf16 v[104:107], v[148:151], v[196:199], v[104:107]
	v_mfma_f32_16x16x32_bf16 v[100:103], v[156:159], v[196:199], v[100:103]
	v_mfma_f32_16x16x32_bf16 v[88:91], v[148:151], v[204:207], v[88:91]
	v_mfma_f32_16x16x32_bf16 v[84:87], v[156:159], v[204:207], v[84:87]
	v_mfma_f32_16x16x32_bf16 v[136:139], v[152:155], v[168:171], v[136:139]
	v_mfma_f32_16x16x32_bf16 v[132:135], v[160:163], v[168:171], v[132:135]
	v_mfma_f32_16x16x32_bf16 v[120:123], v[152:155], v[176:179], v[120:123]
	v_mfma_f32_16x16x32_bf16 v[116:119], v[160:163], v[176:179], v[116:119]
	v_mfma_f32_16x16x32_bf16 v[104:107], v[152:155], v[200:203], v[104:107]
	v_mfma_f32_16x16x32_bf16 v[100:103], v[160:163], v[200:203], v[100:103]
	v_mfma_f32_16x16x32_bf16 v[88:91], v[152:155], v[208:211], v[88:91]
	v_mfma_f32_16x16x32_bf16 v[84:87], v[160:163], v[208:211], v[84:87]
	s_barrier
; #define PG8_STAGE(bufoff, gbase, voff) do { _Pragma("unroll") for (int _i = 0; _i < 2; ++_i) \
;         __builtin_amdgcn_global_load_lds((const unsigned*)((const char*)(gbase) + (voff)[_i]), (PG8_LAS unsigned*)(lds + (bufoff) + ldsw + _i * 8192), 16, 0, 0); } while (0)
; #define PG8_LDA(dst, b, h) do { _Pragma("unroll") for (int m = 0; m < 4; ++m) _Pragma("unroll") for (int k = 0; k < 2; ++k) dst[m][k] = *(const PG8_LAS bf16x8*)(lds + PG8_SA(b, h) + aoff + m * 2048 + k * 1024); } while (0)
; #define PG8_MMA(ai, bj, At, Bt) do { __builtin_amdgcn_s_setprio(1); _Pragma("unroll") for (int m = 0; m < 4; ++m) _Pragma("unroll") for (int n = 0; n < 2; ++n) _Pragma("unroll") for (int k = 0; k < 2; ++k) \
;         acc[ai][bj][m][n] = __builtin_amdgcn_mfma_f32_16x16x32_bf16(Bt[n][k], At[m][k], acc[ai][bj][m][n], 0, 0, 0); __builtin_amdgcn_s_setprio(0); } while (0)
; #define PG8_WAIT_V(n) asm volatile("s_waitcnt vmcnt(" #n ")" ::: "memory")
; #define PG8_WAIT_L(n) asm volatile("s_waitcnt lgkmcnt(" #n ")" ::: "memory")
; #define PG8_BAR __builtin_amdgcn_s_barrier()
; #define PG8_SCHED __builtin_amdgcn_sched_barrier(0)
;     __device__ __forceinline__ void operator()(const f32x4 (&acc)[2][2][4][2], const Unit& u, int wr, int wc, int fr, int fq) const {
;         const int row0 = u.pm * BM + wr * 64 + fr; const int col0 = u.pn * BM + wc * 64 + 8 * fq;
;         const int seg = (mode == 1) ? (u.pn >> 1) : 3;
;         const bool qk = (mode == 2) && (u.pn < 5); const float* gn = (u.pn < 4) ? qn : kn; const float qsc = (u.pn < 4) ? 0.125f : 1.0f;
;         f32x4 bv[2][2];
; #pragma unroll
;         for (int bj = 0; bj < 2; ++bj)
; #pragma unroll
;             for (int n = 0; n < 2; ++n) bv[bj][n] = bias ? *(const f32x4*)(bias + col0 + bj * 32 + 4 * n) : (f32x4){0.f, 0.f, 0.f, 0.f};
; template <class Epi, class Sched, bool ALIGN_EPI = false, bool SP2 = false>
; __device__ __forceinline__ void gemm_phase(PG8_LAS unsigned char* lds, const Gemm g, const Sched& S, const Epi& E, const int tid_) {
;     ...
;         for (int t = 0; t < nt; t += 2) {
;     ...
;             PG8_LDA(At, 1, 1); PG8_STAGE(PG8_SB(1, 0), b3, voffB); PG8_STAGE(PG8_SB(1, 1), b3 + hstepB, voffB); PG8_STAGE(PG8_SA(1, 0), a3, voffA);
;             PG8_WAIT_V(8); PG8_WAIT_L(0); PG8_BAR; PG8_MMA(1, 0, At, B0); PG8_MMA(1, 1, At, B1); PG8_BAR; PG8_SCHED;
	s_mov_b32 m0, s64
	v_lshl_add_u64 v[212:213], v[212:213], 0, s[96:97]
	ds_read_b128 v[164:167], v216 offset:49152
	ds_read_b128 v[168:171], v216 offset:50176
	ds_read_b128 v[172:175], v216 offset:51200
	ds_read_b128 v[176:179], v216 offset:52224
	ds_read_b128 v[196:199], v216 offset:53248
	ds_read_b128 v[200:203], v216 offset:54272
	ds_read_b128 v[204:207], v216 offset:55296
	ds_read_b128 v[208:211], v216 offset:56320
	global_load_lds_dwordx4 v[212:213], off
	s_mov_b32 m0, s65
	v_lshl_add_u64 v[212:213], v[218:219], 0, s[96:97]
	global_load_lds_dwordx4 v[212:213], off
	s_mov_b32 m0, s69
	v_lshl_add_u64 v[212:213], v[220:221], 0, s[96:97]
	global_load_lds_dwordx4 v[212:213], off
	s_mov_b32 m0, s70
	v_lshl_add_u64 v[212:213], v[222:223], 0, s[96:97]
	global_load_lds_dwordx4 v[212:213], off
	s_mov_b32 m0, s66
	v_lshl_add_u64 v[212:213], v[224:225], 0, s[96:97]
	global_load_lds_dwordx4 v[212:213], off
	s_mov_b32 m0, s67
	v_lshl_add_u64 v[212:213], v[226:227], 0, s[96:97]
	global_load_lds_dwordx4 v[212:213], off
	s_waitcnt vmcnt(8)
	s_waitcnt lgkmcnt(0)
	s_barrier
	s_waitcnt lgkmcnt(0)
	v_mfma_f32_16x16x32_bf16 v[80:83], v[52:55], v[164:167], v[80:83]
	v_mfma_f32_16x16x32_bf16 v[76:79], v[68:71], v[164:167], v[76:79]
	v_mfma_f32_16x16x32_bf16 v[64:67], v[52:55], v[172:175], v[64:67]
	v_mfma_f32_16x16x32_bf16 v[60:63], v[68:71], v[172:175], v[60:63]
	v_mfma_f32_16x16x32_bf16 v[32:35], v[52:55], v[196:199], v[32:35]
	v_mfma_f32_16x16x32_bf16 v[28:31], v[68:71], v[196:199], v[28:31]
	v_mfma_f32_16x16x32_bf16 v[16:19], v[52:55], v[204:207], v[16:19]
	v_mfma_f32_16x16x32_bf16 v[12:15], v[68:71], v[204:207], v[12:15]
	v_mfma_f32_16x16x32_bf16 v[80:83], v[56:59], v[168:171], v[80:83]
	v_mfma_f32_16x16x32_bf16 v[76:79], v[72:75], v[168:171], v[76:79]
	v_mfma_f32_16x16x32_bf16 v[64:67], v[56:59], v[176:179], v[64:67]
	v_mfma_f32_16x16x32_bf16 v[60:63], v[72:75], v[176:179], v[60:63]
	v_mfma_f32_16x16x32_bf16 v[32:35], v[56:59], v[200:203], v[32:35]
	v_mfma_f32_16x16x32_bf16 v[28:31], v[72:75], v[200:203], v[28:31]
	v_mfma_f32_16x16x32_bf16 v[16:19], v[56:59], v[208:211], v[16:19]
	v_mfma_f32_16x16x32_bf16 v[12:15], v[72:75], v[208:211], v[12:15]
	v_mfma_f32_16x16x32_bf16 v[36:39], v[148:151], v[164:167], v[36:39]
	v_mfma_f32_16x16x32_bf16 v[72:75], v[152:155], v[168:171], v[36:39]
	v_mfma_f32_16x16x32_bf16 v[36:39], v[156:159], v[164:167], v[40:43]
	v_mfma_f32_16x16x32_bf16 v[68:71], v[160:163], v[168:171], v[36:39]
	v_mfma_f32_16x16x32_bf16 v[36:39], v[148:151], v[172:175], v[48:51]
	v_mfma_f32_16x16x32_bf16 v[52:55], v[152:155], v[176:179], v[36:39]
	v_mfma_f32_16x16x32_bf16 v[36:39], v[156:159], v[172:175], v[44:47]
	v_mfma_f32_16x16x32_bf16 v[24:27], v[148:151], v[196:199], v[24:27]
	v_mfma_f32_16x16x32_bf16 v[20:23], v[156:159], v[196:199], v[20:23]
	v_mfma_f32_16x16x32_bf16 v[8:11], v[148:151], v[204:207], v[8:11]
	v_mfma_f32_16x16x32_bf16 v[4:7], v[156:159], v[204:207], v[4:7]
	v_mfma_f32_16x16x32_bf16 v[44:47], v[160:163], v[176:179], v[36:39]
	v_mfma_f32_16x16x32_bf16 v[24:27], v[152:155], v[200:203], v[24:27]
	v_mfma_f32_16x16x32_bf16 v[20:23], v[160:163], v[200:203], v[20:23]
	v_mfma_f32_16x16x32_bf16 v[8:11], v[152:155], v[208:211], v[8:11]
	v_mfma_f32_16x16x32_bf16 v[4:7], v[160:163], v[208:211], v[4:7]
	s_barrier
	s_add_u32 s12, s12, 0x100
	s_addc_u32 s13, s13, 0
	s_add_u32 s2, s2, 0x100
	s_addc_u32 s3, s3, 0
	s_cmp_ge_u32 s46, s73
	s_mov_b32 s14, s46
	s_cbranch_scc0 .LBB0_528
	s_and_b64 vcc, exec, s[36:37]
	s_cbranch_vccnz .Lepi3_old
	s_and_b64 vcc, exec, s[40:41]
	s_cbranch_vccnz .Lepi3_old
	v_lshl_add_u32 v245, s81, 8, v187
	v_lshl_or_b32 v217, s80, 8, v215
	v_lshlrev_b32_e32 v247, 11, v245
	v_lshl_add_u32 v212, v217, 1, v247
	v_lshlrev_b32_e32 v249, 2, v217
	v_mov_b32_e32 v36, 0
	v_mov_b32_e32 v37, 0
	v_mov_b32_e32 v38, 0
	v_mov_b32_e32 v39, 0
	v_mov_b32_e32 v40, 0
	v_mov_b32_e32 v41, 0
	v_mov_b32_e32 v42, 0
	v_mov_b32_e32 v43, 0
	v_mov_b32_e32 v48, 0
	v_mov_b32_e32 v49, 0
	v_mov_b32_e32 v50, 0
	v_mov_b32_e32 v51, 0
	v_mov_b32_e32 v56, 0
	v_mov_b32_e32 v57, 0
	v_mov_b32_e32 v58, 0
	v_mov_b32_e32 v59, 0
	s_and_b64 vcc, exec, s[34:35]
	s_cbranch_vccz .Lepi3_nobias
	global_load_dwordx4 v[56:59], v249, s[18:19]
	global_load_dwordx4 v[48:51], v249, s[18:19] offset:16
	global_load_dwordx4 v[40:43], v249, s[18:19] offset:128
	global_load_dwordx4 v[36:39], v249, s[18:19] offset:144
